# PEER phase rewritten: expert tables stored slice-major (8 column slices of 128), per-wave time-sliced gather so each slice stays L2-resident; dots/idx in LDS
# speedup vs baseline: 1.1053x; 1.1053x over previous
; DI void phase_tables(const Params& p, int l, int bid, int nblk) {
;     ...
;   for (int e = gtid; e < 2 * 16384 * 64; e += gn) {
;     const int which = e / (16384 * 64), r = e % (16384 * 64);
;     const float sc = which ? V_SCALE : U_SCALE;
;     const float* src = (which ? p.in[I_PV] : p.in[I_PU]) + (size_t)l * 16384 * 1024 + (size_t)r * 16;
;     u32 o[4];
; #pragma unroll
;     for (int q = 0; q < 4; ++q) {
;       const float4 a = *(const float4*)(src + q * 4);
;       int v = __builtin_amdgcn_cvt_pk_fp8_f32(a.x * sc, a.y * sc, 0, false);
;       v = __builtin_amdgcn_cvt_pk_fp8_f32(a.z * sc, a.w * sc, v, true);
;       o[q] = (u32)v;
;     }
;     uint4 ov = {o[0], o[1], o[2], o[3]};
;     *(uint4*)&dst[(size_t)e * 16] = ov;
;   }
.LBB0_1332:
	v_lshrrev_b32_e32 v24, 20, v0
	v_bfe_u32 v25, v0, 3, 3
	v_lshlrev_b32_e32 v24, 24, v24
	v_lshl_or_b32 v24, v25, 21, v24
	v_bfe_u32 v25, v0, 6, 14
	v_lshl_or_b32 v24, v25, 7, v24
	v_and_b32_e32 v25, 7, v0
	v_lshl_or_b32 v24, v25, 4, v24
	v_ashrrev_i32_e32 v1, 31, v0
	v_lshrrev_b32_e32 v1, 12, v1
	v_add_u32_e32 v1, v0, v1
	v_and_b32_e32 v1, 0xfff00000, v1
	v_sub_u32_e32 v4, v0, v1
	v_add_u32_e32 v1, 0xfffff, v0
	v_cmp_gt_u32_e32 vcc, s19, v1
	v_mov_b32_e32 v5, s91
	v_mov_b32_e32 v6, s89
	v_cndmask_b32_e32 v7, v5, v6, vcc
	v_mov_b32_e32 v5, s90
	v_mov_b32_e32 v6, s88
	v_cndmask_b32_e32 v6, v5, v6, vcc
	v_ashrrev_i32_e32 v5, 31, v4
	v_lshl_add_u64 v[6:7], s[86:87], 2, v[6:7]
	v_lshlrev_b64 v[4:5], 6, v[4:5]
	v_lshl_add_u64 v[16:17], v[6:7], 0, v[4:5]
	global_load_dwordx4 v[4:7], v[16:17], off offset:48
	global_load_dwordx4 v[8:11], v[16:17], off offset:32
	global_load_dwordx4 v[12:15], v[16:17], off offset:16
	s_nop 0
	global_load_dwordx4 v[16:19], v[16:17], off
	v_mov_b32_e32 v1, 0x42800000
	v_cndmask_b32_e32 v1, 4.0, v1, vcc
	v_add_u32_e32 v0, s18, v0
	v_cmp_lt_i32_e32 vcc, s19, v0
	s_or_b64 s[36:37], vcc, s[36:37]
	s_waitcnt vmcnt(3)
	v_mul_f32_e32 v4, v1, v4
	s_waitcnt vmcnt(2)
	v_mul_f32_e32 v8, v1, v8
	s_waitcnt vmcnt(1)
	v_mul_f32_e32 v12, v1, v12
	s_waitcnt vmcnt(0)
	v_mul_f32_e32 v20, v16, v1
	v_mul_f32_e32 v17, v17, v1
	v_mov_b32_e32 v16, v173
	v_cvt_pk_fp8_f32 v16, v20, v17
	v_mul_f32_e32 v17, v1, v18
	v_mul_f32_e32 v18, v1, v19
	v_mul_f32_e32 v13, v1, v13
	v_cvt_pk_fp8_f32 v16, v17, v18 op_sel:[0,0,1]
	v_mov_b32_e32 v17, v173
	v_mul_f32_e32 v9, v1, v9
	v_mov_b32_e32 v18, v173
	v_mul_f32_e32 v5, v1, v5
	v_mov_b32_e32 v19, v173
	v_cvt_pk_fp8_f32 v17, v12, v13
	v_cvt_pk_fp8_f32 v18, v8, v9
	v_cvt_pk_fp8_f32 v19, v4, v5
	v_mul_f32_e32 v12, v1, v14
	v_mul_f32_e32 v13, v1, v15
	v_mul_f32_e32 v8, v1, v10
	v_mul_f32_e32 v9, v1, v11
	v_mul_f32_e32 v4, v1, v6
	v_mul_f32_e32 v1, v1, v7
	v_cvt_pk_fp8_f32 v17, v12, v13 op_sel:[0,0,1]
	v_cvt_pk_fp8_f32 v18, v8, v9 op_sel:[0,0,1]
	v_cvt_pk_fp8_f32 v19, v4, v1 op_sel:[0,0,1]
	global_store_dwordx4 v24, v[16:19], s[16:17]
	v_lshl_add_u64 v[2:3], v[2:3], 0, s[22:23]
	s_andn2_b64 exec, exec, s[36:37]
	s_cbranch_execnz .LBB0_1332

; DI int TID() { int t = threadIdx.x; asm volatile("" : "+v"(t)); return t; }
; DI void phase_peer(const Params& p, int l, int bid, int nblk) {
;   const int w = TID() >> 6;
;   const float* TV = WSP(const float, OFF_TV);
;   const int* TI = WSP(const int, OFF_TI);
;   const u16* H2 = WSP(const u16, OFF_ACT);
;   const unsigned char* UB = WSP(const unsigned char, OFF_XBCA);
;   const unsigned char* VB = UB + (size_t)16384 * 1024;
;   const float* gfin = p.in[I_GF];
;   for (int row = bid * 4 + w; row < ROWS; row += nblk * 4) {
;     const int b = row / TPB, pos = row % TPB;
;     if (l == 1 && pos < CTXL) continue;
;     const int lane = TID() & 63;
.LBB0_1505:
	s_or_b64 exec, exec, s[0:1]
	s_waitcnt lgkmcnt(0)
	v_mov_b32_e32 v0, v218
	s_barrier
	v_lshrrev_b32_e32 v0, 6, v218
	v_readlane_b32 s67, v255, 58
	v_and_b32_e32 v1, 63, v218
	v_readfirstlane_b32 s72, v0
	s_add_i32 s67, s67, s72
	s_cmp_eq_u32 s72, 3
	s_cbranch_scc0 .Lpeer_nosave
	v_mov_b32_e32 v2, 0x11fe0
	ds_read_b32 v3, v2
	ds_read_b32 v4, v2 offset:4
	s_waitcnt lgkmcnt(0)
	v_readfirstlane_b32 s73, v3
	v_readfirstlane_b32 s74, v4
.Lpeer_nosave:
	s_mul_i32 s0, s72, 0x4800
	v_lshlrev_b32_e32 v1, 4, v1
	v_add_u32_e32 v1, s0, v1
	v_mov_b32_e32 v4, 0
	v_mov_b32_e32 v5, 0
	v_mov_b32_e32 v6, 0
	v_mov_b32_e32 v7, 0
	ds_write_b128 v1, v[4:7] offset:9216
	ds_write_b128 v1, v[4:7] offset:10240
	ds_write_b128 v1, v[4:7] offset:11264
	ds_write_b128 v1, v[4:7] offset:12288
	ds_write_b128 v1, v[4:7] offset:13312
	ds_write_b128 v1, v[4:7] offset:14336
	ds_write_b128 v1, v[4:7] offset:15360
	ds_write_b128 v1, v[4:7] offset:16384
	ds_write_b128 v1, v[4:7] offset:17408
	v_mov_b32_e32 v0, v218
	s_mov_b32 s55, 0
	s_mov_b32 s66, 0
	v_readlane_b32 s0, v255, 58
	v_ashrrev_i32_e32 v0, 6, v0
	v_readlane_b32 s1, v255, 59
	v_add_u32_e32 v64, s0, v0
	s_mov_b32 s0, 0x9000
	v_cmp_gt_i32_e32 vcc, s0, v64
	s_and_saveexec_b64 s[50:51], vcc
	s_cbranch_execz .LBB0_1558
	s_mov_b64 s[62:63], 0
	s_branch .LBB0_1509

; template <int CTRL> DI int dpp_i(int v) { return __builtin_amdgcn_mov_dpp(v, CTRL, 0xF, 0xF, true); }
; DI void phase_peer(const Params& p, int l, int bid, int nblk) {
;     ...
;     for (int s = 0; s < 7; ++s) {
;       const int c = sub + 8 * s;
;       if (c < 50) {
;         const u32 u = __float_as_uint(tv1[cand_a(c)] + tv2[cand_b(c)]);
;         const u32 ord = (u & 0x80000000u) ? ~u : (u | 0x80000000u);
;         ck[s] = (ord & ~63u) | (u32)(63 - c);
;       } else ck[s] = 0u;
;     }
;     float w0v = 0.f, w1v = 0.f, mx = 0.f;
;     int w0c = 0, w1c = 0;
;     u32 prevk = 0xFFFFFFFFu;
; #pragma unroll
;     for (int r = 0; r < 16; ++r) {
;       u32 m = 0u;
; #pragma unroll
;       for (int s = 0; s < 7; ++s) { const u32 d = ck[s] - prevk; m = d > m ? d : m; }
;       { const u32 ov = (u32)dpp_i<DPP_XOR1>((int)m); m = ov > m ? ov : m; }
;       { const u32 ov = (u32)dpp_i<DPP_XOR2>((int)m); m = ov > m ? ov : m; }
;       { const u32 ov = (u32)dpp_i<DPP_MIRROR8>((int)m); m = ov > m ? ov : m; }
;       const u32 best = prevk + m;
;       prevk = best;
;       const u32 ordv = best & ~63u;
;       const float bv = __uint_as_float((ordv & 0x80000000u) ? (ordv & 0x7FFFFFFFu) : ~ordv);
;       const int bc = 63 - (int)(best & 63u);
;       if (r == 0) mx = bv;
;       if (sub == (r & 7)) {
;         if (r < 8) { w0v = bv; w0c = bc; } else { w1v = bv; w1c = bc; }
;       }
.LBB0_1512:
	s_or_b64 exec, exec, s[34:35]
	s_waitcnt vmcnt(6)
	v_pk_add_f32 v[4:5], v[0:1], v[2:3] op_sel_hi:[0,1]
	v_not_b32_e32 v0, v5
	v_or_b32_e32 v2, 0x80000000, v5
	v_cmp_gt_i32_e64 s[0:1], 0, v5
	v_or_b32_e32 v5, 0x80000000, v4
	v_or_b32_e32 v9, 8, v20
	v_cndmask_b32_e64 v0, v2, v0, s[0:1]
	v_and_b32_e32 v0, 0xffffffc0, v0
	v_sub_u32_e32 v21, v0, v20
	v_not_b32_e32 v0, v4
	v_cmp_gt_i32_e64 s[0:1], 0, v4
	v_mov_b32_e32 v13, v1
	v_or_b32_e32 v23, 24, v20
	v_cndmask_b32_e64 v0, v5, v0, s[0:1]
	v_and_b32_e32 v0, 0xffffffc0, v0
	v_sub_u32_e32 v22, v0, v9
	v_mov_b32_e32 v9, v3
	s_waitcnt vmcnt(4)
	v_pk_add_f32 v[0:1], v[8:9], v[12:13]
	v_or_b32_e32 v5, 16, v20
	v_not_b32_e32 v3, v1
	v_or_b32_e32 v8, 0x80000000, v1
	v_cmp_gt_i32_e64 s[0:1], 0, v1
	v_or_b32_e32 v12, 32, v20
	v_or_b32_e32 v13, 40, v20
	v_cndmask_b32_e64 v1, v8, v3, s[0:1]
	v_and_b32_e32 v1, 0xffffffc0, v1
	v_sub_u32_e32 v8, v1, v5
	v_not_b32_e32 v1, v0
	v_or_b32_e32 v5, 0x80000000, v0
	v_cmp_gt_i32_e64 s[0:1], 0, v0
	v_add_u32_e32 v3, 63, v8
	v_add_u32_e32 v8, 64, v8
	v_cndmask_b32_e64 v0, v5, v1, s[0:1]
	v_and_b32_e32 v0, 0xffffffc0, v0
	v_sub_u32_e32 v9, v0, v23
	s_waitcnt vmcnt(0)
	v_pk_add_f32 v[0:1], v[6:7], v[10:11]
	v_add_u32_e32 v11, 64, v22
	v_not_b32_e32 v6, v1
	v_or_b32_e32 v7, 0x80000000, v1
	v_cmp_gt_i32_e64 s[0:1], 0, v1
	v_or_b32_e32 v10, 0x80000000, v0
	v_add_u32_e32 v5, 63, v9
	v_cndmask_b32_e64 v1, v7, v6, s[0:1]
	v_not_b32_e32 v7, v0
	v_cmp_gt_i32_e64 s[0:1], 0, v0
	v_and_b32_e32 v1, 0xffffffc0, v1
	v_sub_u32_e32 v1, v1, v12
	v_cndmask_b32_e64 v0, v10, v7, s[0:1]
	v_and_b32_e32 v0, 0xffffffc0, v0
	v_add_u32_e32 v10, 64, v21
	v_add_u32_e32 v6, 63, v1
	v_sub_u32_e32 v0, v0, v13
	v_max3_u32 v8, v8, v11, v10
	v_add_u32_e32 v9, 64, v9
	v_add_u32_e32 v1, 64, v1
	v_add_u32_e32 v7, 63, v0
	v_max3_u32 v1, v1, v9, v8
	v_add_u32_e32 v0, 64, v0
	v_add_u32_e32 v8, 1, v19
	v_max3_u32 v0, v8, v0, v1
	v_add_u32_e32 v2, 63, v21
	v_add_u32_e32 v4, 63, v22
	v_max_u32_dpp v0, v0, v0 quad_perm:[1,0,3,2] row_mask:0xf bank_mask:0xf bound_ctrl:1
	v_cmp_eq_u32_e64 s[46:47], 0, v20
	s_nop 0
	v_max_u32_dpp v0, v0, v0 quad_perm:[2,3,0,1] row_mask:0xf bank_mask:0xf bound_ctrl:1
	s_nop 1
	v_max_u32_dpp v0, v0, v0 row_half_mirror row_mask:0xf bank_mask:0xf bound_ctrl:1
	v_add_u32_e32 v9, -1, v0
	v_sub_u32_e32 v10, v2, v9
	v_sub_u32_e32 v11, v4, v9
	v_sub_u32_e32 v12, v3, v9
	v_max3_u32 v10, v12, v11, v10
	v_sub_u32_e32 v11, v5, v9
	v_sub_u32_e32 v12, v6, v9
	v_max3_u32 v10, v12, v11, v10
	v_sub_u32_e32 v11, v7, v9
	v_sub_u32_e32 v12, v19, v9
	v_max3_u32 v10, v12, v11, v10
	v_and_b32_e32 v0, 0x7fffffc0, v9
	v_bitop3_b32 v1, v9, 63, v9 bitop3:0xcf
	v_max_u32_dpp v10, v10, v10 quad_perm:[1,0,3,2] row_mask:0xf bank_mask:0xf bound_ctrl:1
	v_cmp_gt_i32_e64 s[0:1], 0, v9
	s_nop 0
	v_max_u32_dpp v10, v10, v10 quad_perm:[2,3,0,1] row_mask:0xf bank_mask:0xf bound_ctrl:1
	v_cndmask_b32_e64 v1, v1, v0, s[0:1]
	v_bitop3_b32 v0, v9, 63, v9 bitop3:0xc
	v_max_u32_dpp v10, v10, v10 row_half_mirror row_mask:0xf bank_mask:0xf bound_ctrl:1
	v_cndmask_b32_e64 v0, 0, v0, s[46:47]
	v_cndmask_b32_e64 v8, 0, v1, s[46:47]
	v_add_u32_e32 v9, v10, v9
	s_and_saveexec_b64 s[34:35], vcc
	v_and_b32_e32 v0, 0x7fffffc0, v9
	v_bitop3_b32 v8, v9, 63, v9 bitop3:0xcf
	v_cmp_gt_i32_e64 s[0:1], 0, v9
	s_nop 1
	v_cndmask_b32_e64 v8, v8, v0, s[0:1]
	v_bitop3_b32 v0, v9, 63, v9 bitop3:0xc
	s_or_b64 exec, exec, s[34:35]
	v_sub_u32_e32 v10, v2, v9
	v_sub_u32_e32 v11, v4, v9
	v_sub_u32_e32 v12, v3, v9
	v_max3_u32 v10, v12, v11, v10
	v_sub_u32_e32 v11, v5, v9
	v_sub_u32_e32 v12, v6, v9
	v_max3_u32 v10, v12, v11, v10
	v_sub_u32_e32 v11, v7, v9
	v_sub_u32_e32 v12, v19, v9
	v_max3_u32 v10, v12, v11, v10
	v_cmp_eq_u32_e64 s[0:1], 2, v20
	s_nop 0
	v_max_u32_dpp v10, v10, v10 quad_perm:[1,0,3,2] row_mask:0xf bank_mask:0xf bound_ctrl:1
	s_nop 1
	v_max_u32_dpp v10, v10, v10 quad_perm:[2,3,0,1] row_mask:0xf bank_mask:0xf bound_ctrl:1
	s_nop 1
	v_max_u32_dpp v10, v10, v10 row_half_mirror row_mask:0xf bank_mask:0xf bound_ctrl:1
	v_add_u32_e32 v9, v10, v9
	s_and_saveexec_b64 s[34:35], s[0:1]
	v_and_b32_e32 v0, 0x7fffffc0, v9
	v_bitop3_b32 v8, v9, 63, v9 bitop3:0xcf
	v_cmp_gt_i32_e64 s[36:37], 0, v9
	s_nop 1
	v_cndmask_b32_e64 v8, v8, v0, s[36:37]
	v_bitop3_b32 v0, v9, 63, v9 bitop3:0xc
	s_or_b64 exec, exec, s[34:35]
	v_sub_u32_e32 v10, v2, v9
	v_sub_u32_e32 v11, v4, v9
	v_sub_u32_e32 v12, v3, v9
	v_max3_u32 v10, v12, v11, v10
	v_sub_u32_e32 v11, v5, v9
	v_sub_u32_e32 v12, v6, v9
	v_max3_u32 v10, v12, v11, v10
	v_sub_u32_e32 v11, v7, v9
	v_sub_u32_e32 v12, v19, v9
	v_max3_u32 v10, v12, v11, v10
	v_cmp_eq_u32_e64 s[36:37], 3, v20
	s_nop 0
	v_max_u32_dpp v10, v10, v10 quad_perm:[1,0,3,2] row_mask:0xf bank_mask:0xf bound_ctrl:1
	s_nop 1
	v_max_u32_dpp v10, v10, v10 quad_perm:[2,3,0,1] row_mask:0xf bank_mask:0xf bound_ctrl:1
	s_nop 1
	v_max_u32_dpp v10, v10, v10 row_half_mirror row_mask:0xf bank_mask:0xf bound_ctrl:1
	v_add_u32_e32 v9, v10, v9
	s_and_saveexec_b64 s[34:35], s[36:37]
	v_and_b32_e32 v0, 0x7fffffc0, v9
	v_bitop3_b32 v8, v9, 63, v9 bitop3:0xcf
	v_cmp_gt_i32_e64 s[38:39], 0, v9
	s_nop 1
	v_cndmask_b32_e64 v8, v8, v0, s[38:39]
	v_bitop3_b32 v0, v9, 63, v9 bitop3:0xc
	s_or_b64 exec, exec, s[34:35]
	v_sub_u32_e32 v10, v2, v9
	v_sub_u32_e32 v11, v4, v9
	v_sub_u32_e32 v12, v3, v9
	v_max3_u32 v10, v12, v11, v10
	v_sub_u32_e32 v11, v5, v9
	v_sub_u32_e32 v12, v6, v9
	v_max3_u32 v10, v12, v11, v10
	v_sub_u32_e32 v11, v7, v9
	v_sub_u32_e32 v12, v19, v9
	v_max3_u32 v10, v12, v11, v10
	v_cmp_eq_u32_e64 s[38:39], 4, v20
	s_nop 0
	v_max_u32_dpp v10, v10, v10 quad_perm:[1,0,3,2] row_mask:0xf bank_mask:0xf bound_ctrl:1
	s_nop 1
; template <int CTRL> DI int dpp_i(int v) { return __builtin_amdgcn_mov_dpp(v, CTRL, 0xF, 0xF, true); }
; DI void phase_peer(const Params& p, int l, int bid, int nblk) {
;     ...
; #pragma unroll
;     for (int r = 0; r < 16; ++r) {
;       u32 m = 0u;
; #pragma unroll
;       for (int s = 0; s < 7; ++s) { const u32 d = ck[s] - prevk; m = d > m ? d : m; }
;       { const u32 ov = (u32)dpp_i<DPP_XOR1>((int)m); m = ov > m ? ov : m; }
;       { const u32 ov = (u32)dpp_i<DPP_XOR2>((int)m); m = ov > m ? ov : m; }
;       { const u32 ov = (u32)dpp_i<DPP_MIRROR8>((int)m); m = ov > m ? ov : m; }
;       const u32 best = prevk + m;
;       prevk = best;
;       const u32 ordv = best & ~63u;
;       const float bv = __uint_as_float((ordv & 0x80000000u) ? (ordv & 0x7FFFFFFFu) : ~ordv);
;       const int bc = 63 - (int)(best & 63u);
;       if (r == 0) mx = bv;
;       if (sub == (r & 7)) {
;         if (r < 8) { w0v = bv; w0c = bc; } else { w1v = bv; w1c = bc; }
;       }
	v_max_u32_dpp v10, v10, v10 quad_perm:[2,3,0,1] row_mask:0xf bank_mask:0xf bound_ctrl:1
	s_nop 1
	v_max_u32_dpp v10, v10, v10 row_half_mirror row_mask:0xf bank_mask:0xf bound_ctrl:1
	v_add_u32_e32 v9, v10, v9
	s_and_saveexec_b64 s[34:35], s[38:39]
	v_and_b32_e32 v0, 0x7fffffc0, v9
	v_bitop3_b32 v8, v9, 63, v9 bitop3:0xcf
	v_cmp_gt_i32_e64 s[40:41], 0, v9
	s_nop 1
	v_cndmask_b32_e64 v8, v8, v0, s[40:41]
	v_bitop3_b32 v0, v9, 63, v9 bitop3:0xc
	s_or_b64 exec, exec, s[34:35]
	v_sub_u32_e32 v10, v2, v9
	v_sub_u32_e32 v11, v4, v9
	v_sub_u32_e32 v12, v3, v9
	v_max3_u32 v10, v12, v11, v10
	v_sub_u32_e32 v11, v5, v9
	v_sub_u32_e32 v12, v6, v9
	v_max3_u32 v10, v12, v11, v10
	v_sub_u32_e32 v11, v7, v9
	v_sub_u32_e32 v12, v19, v9
	v_max3_u32 v10, v12, v11, v10
	v_cmp_eq_u32_e64 s[40:41], 5, v20
	s_nop 0
	v_max_u32_dpp v10, v10, v10 quad_perm:[1,0,3,2] row_mask:0xf bank_mask:0xf bound_ctrl:1
	s_nop 1
	v_max_u32_dpp v10, v10, v10 quad_perm:[2,3,0,1] row_mask:0xf bank_mask:0xf bound_ctrl:1
	s_nop 1
	v_max_u32_dpp v10, v10, v10 row_half_mirror row_mask:0xf bank_mask:0xf bound_ctrl:1
	v_add_u32_e32 v9, v10, v9
	s_and_saveexec_b64 s[34:35], s[40:41]
	v_and_b32_e32 v0, 0x7fffffc0, v9
	v_bitop3_b32 v8, v9, 63, v9 bitop3:0xcf
	v_cmp_gt_i32_e64 s[42:43], 0, v9
	s_nop 1
	v_cndmask_b32_e64 v8, v8, v0, s[42:43]
	v_bitop3_b32 v0, v9, 63, v9 bitop3:0xc
	s_or_b64 exec, exec, s[34:35]
	v_sub_u32_e32 v10, v2, v9
	v_sub_u32_e32 v11, v4, v9
	v_sub_u32_e32 v12, v3, v9
	v_max3_u32 v10, v12, v11, v10
	v_sub_u32_e32 v11, v5, v9
	v_sub_u32_e32 v12, v6, v9
	v_max3_u32 v10, v12, v11, v10
	v_sub_u32_e32 v11, v7, v9
	v_sub_u32_e32 v12, v19, v9
	v_max3_u32 v10, v12, v11, v10
	v_cmp_eq_u32_e64 s[42:43], 6, v20
	s_nop 0
	v_max_u32_dpp v10, v10, v10 quad_perm:[1,0,3,2] row_mask:0xf bank_mask:0xf bound_ctrl:1
	s_nop 1
	v_max_u32_dpp v10, v10, v10 quad_perm:[2,3,0,1] row_mask:0xf bank_mask:0xf bound_ctrl:1
	s_nop 1
	v_max_u32_dpp v10, v10, v10 row_half_mirror row_mask:0xf bank_mask:0xf bound_ctrl:1
	v_add_u32_e32 v9, v10, v9
	s_and_saveexec_b64 s[34:35], s[42:43]
	v_and_b32_e32 v0, 0x7fffffc0, v9
	v_bitop3_b32 v8, v9, 63, v9 bitop3:0xcf
	v_cmp_gt_i32_e64 s[44:45], 0, v9
	s_nop 1
	v_cndmask_b32_e64 v8, v8, v0, s[44:45]
	v_bitop3_b32 v0, v9, 63, v9 bitop3:0xc
	s_or_b64 exec, exec, s[34:35]
	v_sub_u32_e32 v10, v2, v9
	v_sub_u32_e32 v11, v4, v9
	v_sub_u32_e32 v12, v3, v9
	v_max3_u32 v10, v12, v11, v10
	v_sub_u32_e32 v11, v5, v9
	v_sub_u32_e32 v12, v6, v9
	v_max3_u32 v10, v12, v11, v10
	v_sub_u32_e32 v11, v7, v9
	v_sub_u32_e32 v12, v19, v9
	v_max3_u32 v10, v12, v11, v10
	v_cmp_eq_u32_e64 s[44:45], 7, v20
	s_nop 0
	v_max_u32_dpp v10, v10, v10 quad_perm:[1,0,3,2] row_mask:0xf bank_mask:0xf bound_ctrl:1
	s_nop 1
	v_max_u32_dpp v10, v10, v10 quad_perm:[2,3,0,1] row_mask:0xf bank_mask:0xf bound_ctrl:1
	s_nop 1
	v_max_u32_dpp v10, v10, v10 row_half_mirror row_mask:0xf bank_mask:0xf bound_ctrl:1
	v_add_u32_e32 v9, v10, v9
	s_and_saveexec_b64 s[34:35], s[44:45]
	v_and_b32_e32 v0, 0x7fffffc0, v9
	v_bitop3_b32 v8, v9, 63, v9 bitop3:0xcf
	v_cmp_gt_i32_e64 s[48:49], 0, v9
	s_nop 1
	v_cndmask_b32_e64 v8, v8, v0, s[48:49]
	v_bitop3_b32 v0, v9, 63, v9 bitop3:0xc
	s_or_b64 exec, exec, s[34:35]
	v_sub_u32_e32 v10, v2, v9
	v_sub_u32_e32 v11, v4, v9
	v_sub_u32_e32 v12, v3, v9
	v_max3_u32 v10, v12, v11, v10
	v_sub_u32_e32 v11, v5, v9
	v_sub_u32_e32 v12, v6, v9
	v_max3_u32 v10, v12, v11, v10
	v_sub_u32_e32 v11, v7, v9
	v_sub_u32_e32 v12, v19, v9
	v_max3_u32 v10, v12, v11, v10
	s_nop 1
	v_max_u32_dpp v10, v10, v10 quad_perm:[1,0,3,2] row_mask:0xf bank_mask:0xf bound_ctrl:1
	s_nop 1
	v_max_u32_dpp v10, v10, v10 quad_perm:[2,3,0,1] row_mask:0xf bank_mask:0xf bound_ctrl:1
	s_nop 1
	v_max_u32_dpp v10, v10, v10 row_half_mirror row_mask:0xf bank_mask:0xf bound_ctrl:1
	v_add_u32_e32 v11, v10, v9
	v_mov_b32_e32 v10, 0
	v_mov_b32_e32 v9, 0
	s_and_saveexec_b64 s[34:35], s[46:47]
	v_and_b32_e32 v9, 0x7fffffc0, v11
	v_bitop3_b32 v10, v11, 63, v11 bitop3:0xcf
	v_cmp_gt_i32_e64 s[46:47], 0, v11
	s_nop 1
	v_cndmask_b32_e64 v10, v10, v9, s[46:47]
	v_bitop3_b32 v9, v11, 63, v11 bitop3:0xc
	s_or_b64 exec, exec, s[34:35]
	v_sub_u32_e32 v12, v2, v11
	v_sub_u32_e32 v13, v4, v11
	v_sub_u32_e32 v20, v3, v11
	v_max3_u32 v12, v20, v13, v12
	v_sub_u32_e32 v13, v5, v11
	v_sub_u32_e32 v20, v6, v11
	v_max3_u32 v12, v20, v13, v12
	v_sub_u32_e32 v13, v7, v11
	v_sub_u32_e32 v20, v19, v11
	v_max3_u32 v12, v20, v13, v12
	s_nop 1
	v_max_u32_dpp v12, v12, v12 quad_perm:[1,0,3,2] row_mask:0xf bank_mask:0xf bound_ctrl:1
	s_nop 1
	v_max_u32_dpp v12, v12, v12 quad_perm:[2,3,0,1] row_mask:0xf bank_mask:0xf bound_ctrl:1
	s_nop 1
	v_max_u32_dpp v12, v12, v12 row_half_mirror row_mask:0xf bank_mask:0xf bound_ctrl:1
	v_add_u32_e32 v11, v12, v11
	s_and_saveexec_b64 s[34:35], vcc
	v_and_b32_e32 v9, 0x7fffffc0, v11
	v_bitop3_b32 v10, v11, 63, v11 bitop3:0xcf
	v_cmp_gt_i32_e32 vcc, 0, v11
	s_nop 1
	v_cndmask_b32_e32 v10, v10, v9, vcc
	v_bitop3_b32 v9, v11, 63, v11 bitop3:0xc
	s_or_b64 exec, exec, s[34:35]
	v_sub_u32_e32 v12, v2, v11
	v_sub_u32_e32 v13, v4, v11
	v_sub_u32_e32 v20, v3, v11
	v_max3_u32 v12, v20, v13, v12
	v_sub_u32_e32 v13, v5, v11
	v_sub_u32_e32 v20, v6, v11
	v_max3_u32 v12, v20, v13, v12
	v_sub_u32_e32 v13, v7, v11
	v_sub_u32_e32 v20, v19, v11
	v_max3_u32 v12, v20, v13, v12
	s_nop 1
	v_max_u32_dpp v12, v12, v12 quad_perm:[1,0,3,2] row_mask:0xf bank_mask:0xf bound_ctrl:1
	s_nop 1
	v_max_u32_dpp v12, v12, v12 quad_perm:[2,3,0,1] row_mask:0xf bank_mask:0xf bound_ctrl:1
	s_nop 1
	v_max_u32_dpp v12, v12, v12 row_half_mirror row_mask:0xf bank_mask:0xf bound_ctrl:1
	v_add_u32_e32 v11, v12, v11
	s_and_saveexec_b64 s[34:35], s[0:1]
; template <int CTRL> DI int dpp_i(int v) { return __builtin_amdgcn_mov_dpp(v, CTRL, 0xF, 0xF, true); }
; template <int CTRL> DI float dpp_f(float v) { return __builtin_bit_cast(float, __builtin_amdgcn_mov_dpp(__builtin_bit_cast(int, v), CTRL, 0xF, 0xF, true)); }
; DI void phase_peer(const Params& p, int l, int bid, int nblk) {
;     ...
; #pragma unroll
;     for (int r = 0; r < 16; ++r) {
;       u32 m = 0u;
; #pragma unroll
;       for (int s = 0; s < 7; ++s) { const u32 d = ck[s] - prevk; m = d > m ? d : m; }
;       { const u32 ov = (u32)dpp_i<DPP_XOR1>((int)m); m = ov > m ? ov : m; }
;       { const u32 ov = (u32)dpp_i<DPP_XOR2>((int)m); m = ov > m ? ov : m; }
;       { const u32 ov = (u32)dpp_i<DPP_MIRROR8>((int)m); m = ov > m ? ov : m; }
;       const u32 best = prevk + m;
;       prevk = best;
;       const u32 ordv = best & ~63u;
;       const float bv = __uint_as_float((ordv & 0x80000000u) ? (ordv & 0x7FFFFFFFu) : ~ordv);
;       const int bc = 63 - (int)(best & 63u);
;       if (r == 0) mx = bv;
;       if (sub == (r & 7)) {
;         if (r < 8) { w0v = bv; w0c = bc; } else { w1v = bv; w1c = bc; }
;       }
;     }
;     const float e0 = expf(w0v - mx), e1 = expf(w1v - mx);
;     float es = e0 + e1;
;     es += dpp_f<DPP_XOR1>(es);
;     es += dpp_f<DPP_XOR2>(es);
;     es += dpp_f<DPP_MIRROR8>(es);
;     const float g0 = e0 / es, g1 = e1 / es;
;     int idx0, idx1;
;     {
;       const int gb = lane & ~7;
;       const int a0 = cand_a(w0c), c0 = cand_b(w0c), a1 = cand_a(w1c), c1 = cand_b(w1c);
	v_and_b32_e32 v9, 0x7fffffc0, v11
	v_bitop3_b32 v10, v11, 63, v11 bitop3:0xcf
	v_cmp_gt_i32_e32 vcc, 0, v11
	s_nop 1
	v_cndmask_b32_e32 v10, v10, v9, vcc
	v_bitop3_b32 v9, v11, 63, v11 bitop3:0xc
	s_or_b64 exec, exec, s[34:35]
	v_sub_u32_e32 v12, v2, v11
	v_sub_u32_e32 v13, v4, v11
	v_sub_u32_e32 v20, v3, v11
	v_max3_u32 v12, v20, v13, v12
	v_sub_u32_e32 v13, v5, v11
	v_sub_u32_e32 v20, v6, v11
	v_max3_u32 v12, v20, v13, v12
	v_sub_u32_e32 v13, v7, v11
	v_sub_u32_e32 v20, v19, v11
	v_max3_u32 v12, v20, v13, v12
	s_nop 1
	v_max_u32_dpp v12, v12, v12 quad_perm:[1,0,3,2] row_mask:0xf bank_mask:0xf bound_ctrl:1
	s_nop 1
	v_max_u32_dpp v12, v12, v12 quad_perm:[2,3,0,1] row_mask:0xf bank_mask:0xf bound_ctrl:1
	s_nop 1
	v_max_u32_dpp v12, v12, v12 row_half_mirror row_mask:0xf bank_mask:0xf bound_ctrl:1
	v_add_u32_e32 v11, v12, v11
	s_and_saveexec_b64 s[0:1], s[36:37]
	v_and_b32_e32 v9, 0x7fffffc0, v11
	v_bitop3_b32 v10, v11, 63, v11 bitop3:0xcf
	v_cmp_gt_i32_e32 vcc, 0, v11
	s_nop 1
	v_cndmask_b32_e32 v10, v10, v9, vcc
	v_bitop3_b32 v9, v11, 63, v11 bitop3:0xc
	s_or_b64 exec, exec, s[0:1]
	v_sub_u32_e32 v12, v2, v11
	v_sub_u32_e32 v13, v4, v11
	v_sub_u32_e32 v20, v3, v11
	v_max3_u32 v12, v20, v13, v12
	v_sub_u32_e32 v13, v5, v11
	v_sub_u32_e32 v20, v6, v11
	v_max3_u32 v12, v20, v13, v12
	v_sub_u32_e32 v13, v7, v11
	v_sub_u32_e32 v20, v19, v11
	v_max3_u32 v12, v20, v13, v12
	s_nop 1
	v_max_u32_dpp v12, v12, v12 quad_perm:[1,0,3,2] row_mask:0xf bank_mask:0xf bound_ctrl:1
	s_nop 1
	v_max_u32_dpp v12, v12, v12 quad_perm:[2,3,0,1] row_mask:0xf bank_mask:0xf bound_ctrl:1
	s_nop 1
	v_max_u32_dpp v12, v12, v12 row_half_mirror row_mask:0xf bank_mask:0xf bound_ctrl:1
	v_add_u32_e32 v11, v12, v11
	s_and_saveexec_b64 s[0:1], s[38:39]
	v_and_b32_e32 v9, 0x7fffffc0, v11
	v_bitop3_b32 v10, v11, 63, v11 bitop3:0xcf
	v_cmp_gt_i32_e32 vcc, 0, v11
	s_nop 1
	v_cndmask_b32_e32 v10, v10, v9, vcc
	v_bitop3_b32 v9, v11, 63, v11 bitop3:0xc
	s_or_b64 exec, exec, s[0:1]
	v_sub_u32_e32 v12, v2, v11
	v_sub_u32_e32 v13, v4, v11
	v_sub_u32_e32 v20, v3, v11
	v_max3_u32 v12, v20, v13, v12
	v_sub_u32_e32 v13, v5, v11
	v_sub_u32_e32 v20, v6, v11
	v_max3_u32 v12, v20, v13, v12
	v_sub_u32_e32 v13, v7, v11
	v_sub_u32_e32 v20, v19, v11
	v_max3_u32 v12, v20, v13, v12
	s_nop 1
	v_max_u32_dpp v12, v12, v12 quad_perm:[1,0,3,2] row_mask:0xf bank_mask:0xf bound_ctrl:1
	s_nop 1
	v_max_u32_dpp v12, v12, v12 quad_perm:[2,3,0,1] row_mask:0xf bank_mask:0xf bound_ctrl:1
	s_nop 1
	v_max_u32_dpp v12, v12, v12 row_half_mirror row_mask:0xf bank_mask:0xf bound_ctrl:1
	v_add_u32_e32 v11, v12, v11
	s_and_saveexec_b64 s[0:1], s[40:41]
	v_and_b32_e32 v9, 0x7fffffc0, v11
	v_bitop3_b32 v10, v11, 63, v11 bitop3:0xcf
	v_cmp_gt_i32_e32 vcc, 0, v11
	s_nop 1
	v_cndmask_b32_e32 v10, v10, v9, vcc
	v_bitop3_b32 v9, v11, 63, v11 bitop3:0xc
	s_or_b64 exec, exec, s[0:1]
	v_sub_u32_e32 v12, v2, v11
	v_sub_u32_e32 v13, v4, v11
	v_sub_u32_e32 v20, v3, v11
	v_max3_u32 v12, v20, v13, v12
	v_sub_u32_e32 v13, v5, v11
	v_sub_u32_e32 v20, v6, v11
	v_max3_u32 v12, v20, v13, v12
	v_sub_u32_e32 v13, v7, v11
	v_sub_u32_e32 v20, v19, v11
	v_max3_u32 v12, v20, v13, v12
	s_nop 1
	v_max_u32_dpp v12, v12, v12 quad_perm:[1,0,3,2] row_mask:0xf bank_mask:0xf bound_ctrl:1
	s_nop 1
	v_max_u32_dpp v12, v12, v12 quad_perm:[2,3,0,1] row_mask:0xf bank_mask:0xf bound_ctrl:1
	s_nop 1
	v_max_u32_dpp v12, v12, v12 row_half_mirror row_mask:0xf bank_mask:0xf bound_ctrl:1
	v_add_u32_e32 v11, v12, v11
	s_and_saveexec_b64 s[0:1], s[42:43]
	v_and_b32_e32 v9, 0x7fffffc0, v11
	v_bitop3_b32 v10, v11, 63, v11 bitop3:0xcf
	v_cmp_gt_i32_e32 vcc, 0, v11
	s_nop 1
	v_cndmask_b32_e32 v10, v10, v9, vcc
	v_bitop3_b32 v9, v11, 63, v11 bitop3:0xc
	s_or_b64 exec, exec, s[0:1]
	v_sub_u32_e32 v2, v2, v11
	v_sub_u32_e32 v4, v4, v11
	v_sub_u32_e32 v3, v3, v11
	v_max3_u32 v2, v3, v4, v2
	v_sub_u32_e32 v3, v5, v11
	v_sub_u32_e32 v4, v6, v11
	v_max3_u32 v2, v4, v3, v2
	v_sub_u32_e32 v3, v7, v11
	v_sub_u32_e32 v4, v19, v11
	v_max3_u32 v2, v4, v3, v2
	s_nop 1
	v_max_u32_dpp v2, v2, v2 quad_perm:[1,0,3,2] row_mask:0xf bank_mask:0xf bound_ctrl:1
	s_nop 1
	v_max_u32_dpp v2, v2, v2 quad_perm:[2,3,0,1] row_mask:0xf bank_mask:0xf bound_ctrl:1
	s_nop 1
	v_mov_b32_dpp v3, v2 row_half_mirror row_mask:0xf bank_mask:0xf bound_ctrl:1
	s_and_saveexec_b64 s[0:1], s[44:45]
	v_max_u32_e32 v2, v3, v2
	v_add_u32_e32 v2, v2, v11
	v_and_b32_e32 v3, 0x7fffffc0, v2
	v_bitop3_b32 v4, v2, 63, v2 bitop3:0xcf
	v_cmp_gt_i32_e32 vcc, 0, v2
	v_bitop3_b32 v9, v2, 63, v2 bitop3:0xc
	s_nop 0
	v_cndmask_b32_e32 v10, v4, v3, vcc
	s_or_b64 exec, exec, s[0:1]
	v_sub_f32_e32 v3, v8, v1
	v_mul_f32_e32 v4, 0x3fb8aa3b, v3
	v_fma_f32 v5, v3, s2, -v4
	v_rndne_f32_e32 v6, v4
	v_fmac_f32_e32 v5, 0x32a5705f, v3
	v_sub_f32_e32 v4, v4, v6
	v_add_f32_e32 v4, v4, v5
	v_exp_f32_e32 v4, v4
	v_cvt_i32_f32_e32 v5, v6
	v_cmp_ngt_f32_e32 vcc, s3, v3
	v_sub_f32_e32 v1, v10, v1
	v_mov_b32_e32 v8, 0x11111111
	v_ldexp_f32 v4, v4, v5
	v_cndmask_b32_e32 v4, 0, v4, vcc
	v_cmp_nlt_f32_e32 vcc, s58, v3
	v_mul_f32_e32 v3, 0x3fb8aa3b, v1
	v_rndne_f32_e32 v5, v3
	v_cndmask_b32_e32 v85, v217, v4, vcc
	v_fma_f32 v4, v1, s2, -v3
	v_fmac_f32_e32 v4, 0x32a5705f, v1
	v_sub_f32_e32 v3, v3, v5
	v_add_f32_e32 v3, v3, v4
	v_exp_f32_e32 v3, v3
	v_cvt_i32_f32_e32 v4, v5
	v_cmp_ngt_f32_e32 vcc, s3, v1
	v_mov_b32_e32 v19, 0x76543210
	v_mov_b32_e32 v20, 0xfedcba98
	v_ldexp_f32 v3, v3, v4
	v_cndmask_b32_e32 v3, 0, v3, vcc
	v_cmp_nlt_f32_e32 vcc, s58, v1
	v_mov_b32_e32 v10, 0x33322222
	v_mov_b32_e32 v21, 0x21043210
	v_cndmask_b32_e32 v86, v217, v3, vcc
	v_lshrrev_b32_e32 v3, 3, v0
	v_cmp_eq_u32_e32 vcc, 2, v3
	v_cmp_eq_u32_e64 s[40:41], 1, v3
; template <int CTRL> DI float dpp_f(float v) { return __builtin_bit_cast(float, __builtin_amdgcn_mov_dpp(__builtin_bit_cast(int, v), CTRL, 0xF, 0xF, true)); }
; DI void phase_peer(const Params& p, int l, int bid, int nblk) {
;     ...
;     const float e0 = expf(w0v - mx), e1 = expf(w1v - mx);
;     float es = e0 + e1;
;     es += dpp_f<DPP_XOR1>(es);
;     es += dpp_f<DPP_XOR2>(es);
;     es += dpp_f<DPP_MIRROR8>(es);
;     const float g0 = e0 / es, g1 = e1 / es;
;     int idx0, idx1;
;     {
;       const int gb = lane & ~7;
;       const int a0 = cand_a(w0c), c0 = cand_b(w0c), a1 = cand_a(w1c), c1 = cand_b(w1c);
;       const int p0l = __shfl(t1lo, gb + (a0 & 7)), p0h = __shfl(t1hi, gb + (a0 & 7));
;       const int q0l = __shfl(t2lo, gb + (c0 & 7)), q0h = __shfl(t2hi, gb + (c0 & 7));
;       const int p1l = __shfl(t1lo, gb + (a1 & 7)), p1h = __shfl(t1hi, gb + (a1 & 7));
;       const int q1l = __shfl(t2lo, gb + (c1 & 7)), q1h = __shfl(t2hi, gb + (c1 & 7));
;       idx0 = ((a0 & 8) ? p0h : p0l) * 128 + ((c0 & 8) ? q0h : q0l);
;       idx1 = ((a1 & 8) ? p1h : p1l) * 128 + ((c1 & 8) ? q1h : q1l);
;     }
;     ...
;     const float ga0 = gelu_tanh(act0 * (1.f / U_SCALE)) * g0 * (1.f / V_SCALE);
;     const float ga1 = gelu_tanh(act1 * (1.f / U_SCALE)) * g1 * (1.f / V_SCALE);
	v_cmp_eq_u32_e64 s[0:1], 4, v3
	v_cndmask_b32_e32 v4, 0, v8, vcc
	v_cmp_eq_u32_e32 vcc, 3, v3
	v_cmp_eq_u32_e64 s[36:37], 5, v3
	v_cmp_eq_u32_e64 s[38:39], 6, v3
	v_cndmask_b32_e64 v3, v19, v20, s[40:41]
	v_cndmask_b32_e32 v4, v4, v10, vcc
	v_mov_b32_e32 v11, 0x66554443
	v_cndmask_b32_e32 v3, v3, v21, vcc
	v_mov_b32_e32 v22, 0x10102103
	v_lshrrev_b32_e32 v7, 3, v9
	v_cndmask_b32_e64 v4, v4, v11, s[0:1]
	v_mov_b32_e32 v12, 0xdcba9877
	v_cndmask_b32_e64 v3, v3, v22, s[0:1]
	v_cmp_eq_u32_e32 vcc, 2, v7
	v_cndmask_b32_e64 v4, v4, v12, s[36:37]
	v_mov_b32_e32 v13, 0xfe
	v_cndmask_b32_e64 v3, v3, 16, s[36:37]
	v_cndmask_b32_e32 v8, 0, v8, vcc
	v_cmp_eq_u32_e32 vcc, 3, v7
	v_cmp_eq_u32_e64 s[40:41], 1, v7
	v_add_f32_e32 v1, v85, v86
	v_cndmask_b32_e64 v4, v4, v13, s[38:39]
	v_lshlrev_b32_e32 v0, 2, v0
	v_cndmask_b32_e64 v3, v3, 0, s[38:39]
	v_cndmask_b32_e32 v8, v8, v10, vcc
	v_cmp_eq_u32_e64 s[0:1], 4, v7
	v_cmp_eq_u32_e64 s[36:37], 5, v7
	v_cmp_eq_u32_e64 s[38:39], 6, v7
	v_cndmask_b32_e64 v7, v19, v20, s[40:41]
	v_add_f32_dpp v1, v1, v1 quad_perm:[1,0,3,2] row_mask:0xf bank_mask:0xf bound_ctrl:1
	v_and_b32_e32 v5, 28, v0
	v_cndmask_b32_e64 v8, v8, v11, s[0:1]
	v_cndmask_b32_e32 v7, v7, v21, vcc
	v_add_f32_dpp v87, v1, v1 quad_perm:[2,3,0,1] row_mask:0xf bank_mask:0xf bound_ctrl:1
	v_and_b32_e32 v1, 56, v14
	v_lshrrev_b32_e32 v6, v0, v4
	v_cndmask_b32_e64 v8, v8, v12, s[36:37]
	v_lshlrev_b32_e32 v9, 2, v9
	v_cndmask_b32_e64 v7, v7, v22, s[0:1]
	v_bfe_u32 v4, v4, v5, 3
	v_lshrrev_b32_e32 v0, v0, v3
	v_cndmask_b32_e64 v8, v8, v13, s[38:39]
	v_and_b32_e32 v10, 28, v9
	v_cndmask_b32_e64 v7, v7, 16, s[36:37]
	v_or3_b32 v4, v1, v4, v216
	v_bfe_u32 v3, v3, v5, 3
	v_lshrrev_b32_e32 v11, v9, v8
	v_cndmask_b32_e64 v7, v7, 0, s[38:39]
	v_lshlrev_b32_e32 v4, 2, v4
	v_or3_b32 v3, v1, v3, v216
	v_bfe_u32 v8, v8, v10, 3
	v_lshrrev_b32_e32 v9, v9, v7
	ds_bpermute_b32 v12, v4, v17
	ds_bpermute_b32 v4, v4, v18
	v_lshlrev_b32_e32 v3, 2, v3
	v_or3_b32 v8, v1, v8, v216
	v_bfe_u32 v7, v7, v10, 3
	ds_bpermute_b32 v5, v3, v15
	ds_bpermute_b32 v3, v3, v16
	v_lshlrev_b32_e32 v8, 2, v8
	v_or3_b32 v1, v1, v7, v216
	ds_bpermute_b32 v13, v8, v17
	ds_bpermute_b32 v8, v8, v18
	v_lshlrev_b32_e32 v1, 2, v1
	v_and_b32_e32 v6, 8, v6
	ds_bpermute_b32 v7, v1, v15
	ds_bpermute_b32 v1, v1, v16
	v_and_b32_e32 v0, 8, v0
	v_cmp_eq_u32_e32 vcc, 0, v6
	v_and_b32_e32 v11, 8, v11
	v_and_b32_e32 v9, 8, v9
	s_waitcnt lgkmcnt(6)
	v_cndmask_b32_e32 v10, v4, v12, vcc
	v_cmp_eq_u32_e32 vcc, 0, v0
	v_and_b32_e32 v2, 63, v14
	v_lshlrev_b32_e32 v172, 4, v2
	s_waitcnt lgkmcnt(4)
	v_cndmask_b32_e32 v12, v3, v5, vcc
	v_cmp_eq_u32_e32 vcc, 0, v11
	v_lshlrev_b32_e32 v2, 5, v2
	v_mov_b32_e32 v3, v173
	s_waitcnt lgkmcnt(2)
	v_cndmask_b32_e32 v8, v8, v13, vcc
	v_cmp_eq_u32_e32 vcc, 0, v9
	v_lshl_add_u32 v150, v10, 7, v12
	v_readlane_b32 s0, v255, 40
	s_waitcnt lgkmcnt(0)
	v_cndmask_b32_e32 v9, v1, v7, vcc
	v_lshl_add_u32 v151, v8, 7, v9
	v_mov_b32_dpp v88, v87 row_half_mirror row_mask:0xf bank_mask:0xf bound_ctrl:1
	v_lshrrev_b32_e32 v6, 6, v218
	v_and_b32_e32 v7, 63, v218
	v_add_f32_e32 v0, v87, v88
	v_mul_u32_u24_e32 v6, 0x4800, v6
	v_rcp_f32_e32 v1, v0
	v_lshl_add_u32 v6, v7, 2, v6
	v_fma_f32 v2, -v0, v1, 2.0
	v_mul_f32_e32 v1, v1, v2
	v_mul_f32_e32 v1, 0x3e800000, v1
	v_add_u32_e32 v6, s66, v6
	v_mul_f32_e32 v2, v85, v1
	v_mul_f32_e32 v3, v86, v1
	v_lshlrev_b32_e32 v4, 7, v150
	v_lshlrev_b32_e32 v5, 7, v151
	v_lshlrev_b32_e32 v9, 9, v64
	ds_write_b32 v6, v4
	ds_write_b32 v6, v5 offset:256
	v_lshl_add_u32 v9, v7, 2, v9
	s_add_u32 s16, s96, 0x0
	s_addc_u32 s17, s97, 0
	global_store_dword v9, v2, s[16:17]
	global_store_dword v9, v3, s[16:17] offset:256
	s_add_i32 s55, s55, 1
	s_addk_i32 s66, 0x200
	s_branch .LBB0_1508
.LBB0_1558:
	s_or_b64 exec, exec, s[50:51]
	s_waitcnt vmcnt(0) lgkmcnt(0)
	s_mov_b32 s75, s55
	v_and_b32_e32 v161, 63, v218
	s_mul_i32 s0, s72, 0x4800
	v_and_b32_e32 v0, 7, v161
	v_lshrrev_b32_e32 v1, 3, v161
	v_lshlrev_b32_e32 v160, 4, v0
	v_lshlrev_b32_e32 v165, 5, v0
	v_lshlrev_b32_e32 v2, 6, v1
	v_add_u32_e32 v162, s0, v2
	v_add_u32_e32 v164, 0x2400, v162
	v_bfe_u32 v3, v161, 1, 1
	v_and_b32_e32 v4, 1, v161
	v_bfe_u32 v5, v161, 2, 1
	v_lshlrev_b32_e32 v3, 2, v3
	v_lshl_or_b32 v3, v4, 1, v3
	v_or_b32_e32 v3, v3, v5
	v_lshl_add_u32 v3, v1, 4, v3
	v_lshlrev_b32_e32 v167, 2, v3
	v_add_u32_e32 v163, v164, v167
	v_sub_u32_e32 v163, v163, v2
	v_lshlrev_b32_e32 v4, 4, v0
	v_lshl_add_u32 v4, v1, 1, v4
	v_lshlrev_b32_e32 v166, 2, v4
	v_mov_b32_e32 v168, 0x3d922279
	v_and_b32_e32 v5, 4, v161
	v_and_b32_e32 v6, 1, v161
	v_and_b32_e32 v7, 2, v161
	v_and_b32_e32 v8, 8, v161
	v_cmp_ne_u32_e64 s[34:35], 0, v5
	v_cmp_ne_u32_e64 s[36:37], 0, v6
	v_cmp_ne_u32_e64 s[38:39], 0, v7
	v_cmp_ne_u32_e64 s[40:41], 0, v8
	s_mov_b32 s55, 99
	s_mov_b32 s66, 99
	s_cmp_eq_u64 s[70:71], 0
	s_cbranch_scc1 .Lpeer_noskip
	s_lshr_b32 s55, s67, 8
	s_add_i32 s66, s55, 9
; DI void phase_peer(const Params& p, int l, int bid, int nblk) {
;     ...
;     PEER_LOAD(0, 0, UB)
; #pragma unroll 1
;     for (int k = 0; k < 16; k += 2) {
;       PEER_LOAD(1, k + 1, UB)
;       __builtin_amdgcn_sched_barrier(0);
;       PEER_DOT(0, k)
;       { const int kn = (k + 2 < 16) ? k + 2 : 15; PEER_LOAD(0, kn, UB) }
;       __builtin_amdgcn_sched_barrier(0);
;       PEER_DOT(1, k + 1)
;     }
.Lpeer_noskip:
	s_add_u32 s44, s96, 0xea00000
	s_addc_u32 s45, s97, 0
	s_mov_b32 s42, s44
	s_mov_b32 s43, s45
	s_mov_b32 s46, 0
	s_mov_b32 s47, 0
	s_mov_b32 s50, 0
	s_lshl_b32 s49, s75, 3
	s_cmp_ge_u32 s47, s55
	s_addc_u32 s48, s47, 0
	s_cmp_ge_u32 s48, s66
	s_addc_u32 s48, s48, 0
	s_lshl_b32 s48, s48, 11
	s_add_i32 s48, s48, s67
	s_lshl_b32 s51, s48, 11
	s_add_u32 s78, s6, s51
	s_addc_u32 s79, s7, 0
	global_load_dwordx4 v[96:99], v165, s[78:79]
	global_load_dwordx4 v[100:103], v165, s[78:79] offset:16
	v_add_u32_e32 v144, s50, v162
	ds_read_b128 v[64:67], v144
	ds_read_b128 v[68:71], v144 offset:16
	ds_read_b128 v[72:75], v144 offset:32
	ds_read_b128 v[76:79], v144 offset:48
	s_waitcnt lgkmcnt(0)
	v_add_u32_e32 v0, v64, v160
	v_add_u32_e32 v4, v65, v160
	v_add_u32_e32 v8, v66, v160
	v_add_u32_e32 v12, v67, v160
	v_add_u32_e32 v16, v68, v160
	v_add_u32_e32 v20, v69, v160
	v_add_u32_e32 v24, v70, v160
	v_add_u32_e32 v28, v71, v160
	global_load_dwordx4 v[0:3], v0, s[42:43]
	global_load_dwordx4 v[4:7], v4, s[42:43]
	global_load_dwordx4 v[8:11], v8, s[42:43]
	global_load_dwordx4 v[12:15], v12, s[42:43]
	global_load_dwordx4 v[16:19], v16, s[42:43]
	global_load_dwordx4 v[20:23], v20, s[42:43]
	global_load_dwordx4 v[24:27], v24, s[42:43]
	global_load_dwordx4 v[28:31], v28, s[42:43]
	v_add_u32_e32 v32, v72, v160
	v_add_u32_e32 v36, v73, v160
	v_add_u32_e32 v40, v74, v160
	v_add_u32_e32 v44, v75, v160
	v_add_u32_e32 v48, v76, v160
	v_add_u32_e32 v52, v77, v160
	v_add_u32_e32 v56, v78, v160
	v_add_u32_e32 v60, v79, v160
	global_load_dwordx4 v[32:35], v32, s[42:43]
	global_load_dwordx4 v[36:39], v36, s[42:43]
	global_load_dwordx4 v[40:43], v40, s[42:43]
	global_load_dwordx4 v[44:47], v44, s[42:43]
	global_load_dwordx4 v[48:51], v48, s[42:43]
	global_load_dwordx4 v[52:55], v52, s[42:43]
	global_load_dwordx4 v[56:59], v56, s[42:43]
	global_load_dwordx4 v[60:63], v60, s[42:43]
.Lpeer_u_top:
	s_add_i32 s63, s47, 1
	s_cmp_lt_u32 s63, s75
	s_cselect_b32 s63, s63, 0
	s_cselect_b32 s51, 0, 1
	s_add_i32 s62, s46, s51
	s_cmp_lt_u32 s62, 8
	s_cselect_b32 s62, s62, 7
	s_cselect_b32 s63, s63, s47
	s_cmp_ge_u32 s63, s55
	s_addc_u32 s64, s63, 0
	s_cmp_ge_u32 s64, s66
	s_addc_u32 s64, s64, 0
	s_lshl_b32 s64, s64, 11
	s_add_i32 s64, s64, s67
	s_lshl_b32 s65, s63, 9
	s_lshl_b32 s51, s62, 21
	s_add_u32 s42, s44, s51
	s_addc_u32 s43, s45, 0
	s_lshl_b32 s51, s48, 9
	s_add_u32 s80, s96, s51
	s_addc_u32 s81, s97, 0
	s_lshl_b32 s51, s64, 11
	s_add_u32 s78, s6, s51
	s_addc_u32 s79, s7, 0
	s_lshl_b32 s51, s62, 8
	s_add_u32 s78, s78, s51
	s_addc_u32 s79, s79, 0
	v_add_u32_e32 v144, s65, v162
	ds_read_b128 v[64:67], v144
	ds_read_b128 v[68:71], v144 offset:16
	ds_read_b128 v[72:75], v144 offset:32
	ds_read_b128 v[76:79], v144 offset:48
	v_add_u32_e32 v145, s50, v163
	ds_read2_b32 v[140:141], v145 offset1:8
	global_load_dword v142, v167, s[80:81] sc1
	global_load_dword v143, v167, s[80:81] offset:32 sc1
	s_waitcnt vmcnt(10)
	v_lshlrev_b32_e32 v80, 16, v96
	v_and_b32_e32 v81, 0xffff0000, v96
	v_lshlrev_b32_e32 v82, 16, v97
	v_and_b32_e32 v83, 0xffff0000, v97
	v_lshlrev_b32_e32 v84, 16, v98
	v_and_b32_e32 v85, 0xffff0000, v98
	v_lshlrev_b32_e32 v86, 16, v99
	v_and_b32_e32 v87, 0xffff0000, v99
	v_lshlrev_b32_e32 v88, 16, v100
	v_and_b32_e32 v89, 0xffff0000, v100
	v_lshlrev_b32_e32 v90, 16, v101
	v_and_b32_e32 v91, 0xffff0000, v101
	v_lshlrev_b32_e32 v92, 16, v102
	v_and_b32_e32 v93, 0xffff0000, v102
	v_lshlrev_b32_e32 v94, 16, v103
	v_and_b32_e32 v95, 0xffff0000, v103
	v_cvt_pk_f32_fp8_e32 v[120:121], v0
	v_cvt_pk_f32_fp8_sdwa v[122:123], v0 src0_sel:WORD_1
	v_cvt_pk_f32_fp8_e32 v[124:125], v1
	v_cvt_pk_f32_fp8_sdwa v[126:127], v1 src0_sel:WORD_1
	v_cvt_pk_f32_fp8_e32 v[128:129], v4
	v_cvt_pk_f32_fp8_sdwa v[130:131], v4 src0_sel:WORD_1
	v_cvt_pk_f32_fp8_e32 v[132:133], v5
	v_cvt_pk_f32_fp8_sdwa v[134:135], v5 src0_sel:WORD_1
	v_pk_mul_f32 v[136:137], v[80:81], v[120:121]
	v_pk_mul_f32 v[138:139], v[80:81], v[128:129]
	v_pk_fma_f32 v[136:137], v[82:83], v[122:123], v[136:137]
	v_pk_fma_f32 v[138:139], v[82:83], v[130:131], v[138:139]
	v_pk_fma_f32 v[136:137], v[84:85], v[124:125], v[136:137]
	v_pk_fma_f32 v[138:139], v[84:85], v[132:133], v[138:139]
	v_pk_fma_f32 v[136:137], v[86:87], v[126:127], v[136:137]
	v_pk_fma_f32 v[138:139], v[86:87], v[134:135], v[138:139]
	v_cvt_pk_f32_fp8_e32 v[120:121], v2
	v_cvt_pk_f32_fp8_sdwa v[122:123], v2 src0_sel:WORD_1
	v_cvt_pk_f32_fp8_e32 v[124:125], v3
	v_cvt_pk_f32_fp8_sdwa v[126:127], v3 src0_sel:WORD_1
	v_cvt_pk_f32_fp8_e32 v[128:129], v6
	v_cvt_pk_f32_fp8_sdwa v[130:131], v6 src0_sel:WORD_1
	v_cvt_pk_f32_fp8_e32 v[132:133], v7
	v_cvt_pk_f32_fp8_sdwa v[134:135], v7 src0_sel:WORD_1
	v_pk_fma_f32 v[136:137], v[88:89], v[120:121], v[136:137]
	v_pk_fma_f32 v[138:139], v[88:89], v[128:129], v[138:139]
	v_pk_fma_f32 v[136:137], v[90:91], v[122:123], v[136:137]
	v_pk_fma_f32 v[138:139], v[90:91], v[130:131], v[138:139]
	v_pk_fma_f32 v[136:137], v[92:93], v[124:125], v[136:137]
	v_pk_fma_f32 v[138:139], v[92:93], v[132:133], v[138:139]
	v_pk_fma_f32 v[136:137], v[94:95], v[126:127], v[136:137]
	v_pk_fma_f32 v[138:139], v[94:95], v[134:135], v[138:139]
	v_add_f32_e32 v104, v136, v137
	v_add_f32_e32 v105, v138, v139
	v_cvt_pk_f32_fp8_e32 v[120:121], v8
	v_cvt_pk_f32_fp8_sdwa v[122:123], v8 src0_sel:WORD_1
	v_cvt_pk_f32_fp8_e32 v[124:125], v9
	v_cvt_pk_f32_fp8_sdwa v[126:127], v9 src0_sel:WORD_1
	v_cvt_pk_f32_fp8_e32 v[128:129], v12
	v_cvt_pk_f32_fp8_sdwa v[130:131], v12 src0_sel:WORD_1
	v_cvt_pk_f32_fp8_e32 v[132:133], v13
	v_cvt_pk_f32_fp8_sdwa v[134:135], v13 src0_sel:WORD_1
	v_pk_mul_f32 v[136:137], v[80:81], v[120:121]
	v_pk_mul_f32 v[138:139], v[80:81], v[128:129]
	v_pk_fma_f32 v[136:137], v[82:83], v[122:123], v[136:137]
	v_pk_fma_f32 v[138:139], v[82:83], v[130:131], v[138:139]
	v_pk_fma_f32 v[136:137], v[84:85], v[124:125], v[136:137]
	v_pk_fma_f32 v[138:139], v[84:85], v[132:133], v[138:139]
	v_pk_fma_f32 v[136:137], v[86:87], v[126:127], v[136:137]
	v_pk_fma_f32 v[138:139], v[86:87], v[134:135], v[138:139]
	v_cvt_pk_f32_fp8_e32 v[120:121], v10
	v_cvt_pk_f32_fp8_sdwa v[122:123], v10 src0_sel:WORD_1
	v_cvt_pk_f32_fp8_e32 v[124:125], v11
	v_cvt_pk_f32_fp8_sdwa v[126:127], v11 src0_sel:WORD_1
	v_cvt_pk_f32_fp8_e32 v[128:129], v14
	v_cvt_pk_f32_fp8_sdwa v[130:131], v14 src0_sel:WORD_1
	v_cvt_pk_f32_fp8_e32 v[132:133], v15
	v_cvt_pk_f32_fp8_sdwa v[134:135], v15 src0_sel:WORD_1
	v_pk_fma_f32 v[136:137], v[88:89], v[120:121], v[136:137]
	v_pk_fma_f32 v[138:139], v[88:89], v[128:129], v[138:139]
	v_pk_fma_f32 v[136:137], v[90:91], v[122:123], v[136:137]
	v_pk_fma_f32 v[138:139], v[90:91], v[130:131], v[138:139]
	v_pk_fma_f32 v[136:137], v[92:93], v[124:125], v[136:137]
	v_pk_fma_f32 v[138:139], v[92:93], v[132:133], v[138:139]
	v_pk_fma_f32 v[136:137], v[94:95], v[126:127], v[136:137]
	v_pk_fma_f32 v[138:139], v[94:95], v[134:135], v[138:139]
	v_add_f32_e32 v106, v136, v137
	v_add_f32_e32 v107, v138, v139
	v_cvt_pk_f32_fp8_e32 v[120:121], v16
	v_cvt_pk_f32_fp8_sdwa v[122:123], v16 src0_sel:WORD_1
	v_cvt_pk_f32_fp8_e32 v[124:125], v17
	v_cvt_pk_f32_fp8_sdwa v[126:127], v17 src0_sel:WORD_1
	v_cvt_pk_f32_fp8_e32 v[128:129], v20
	v_cvt_pk_f32_fp8_sdwa v[130:131], v20 src0_sel:WORD_1
	v_cvt_pk_f32_fp8_e32 v[132:133], v21
	v_cvt_pk_f32_fp8_sdwa v[134:135], v21 src0_sel:WORD_1
	v_pk_mul_f32 v[136:137], v[80:81], v[120:121]
	v_pk_mul_f32 v[138:139], v[80:81], v[128:129]
	v_pk_fma_f32 v[136:137], v[82:83], v[122:123], v[136:137]
	v_pk_fma_f32 v[138:139], v[82:83], v[130:131], v[138:139]
	v_pk_fma_f32 v[136:137], v[84:85], v[124:125], v[136:137]
	v_pk_fma_f32 v[138:139], v[84:85], v[132:133], v[138:139]
	v_pk_fma_f32 v[136:137], v[86:87], v[126:127], v[136:137]
	v_pk_fma_f32 v[138:139], v[86:87], v[134:135], v[138:139]
	v_cvt_pk_f32_fp8_e32 v[120:121], v18
	v_cvt_pk_f32_fp8_sdwa v[122:123], v18 src0_sel:WORD_1
	v_cvt_pk_f32_fp8_e32 v[124:125], v19
	v_cvt_pk_f32_fp8_sdwa v[126:127], v19 src0_sel:WORD_1
	v_cvt_pk_f32_fp8_e32 v[128:129], v22
	v_cvt_pk_f32_fp8_sdwa v[130:131], v22 src0_sel:WORD_1
	v_cvt_pk_f32_fp8_e32 v[132:133], v23
	v_cvt_pk_f32_fp8_sdwa v[134:135], v23 src0_sel:WORD_1
	v_pk_fma_f32 v[136:137], v[88:89], v[120:121], v[136:137]
	v_pk_fma_f32 v[138:139], v[88:89], v[128:129], v[138:139]
	v_pk_fma_f32 v[136:137], v[90:91], v[122:123], v[136:137]
	v_pk_fma_f32 v[138:139], v[90:91], v[130:131], v[138:139]
	v_pk_fma_f32 v[136:137], v[92:93], v[124:125], v[136:137]
	v_pk_fma_f32 v[138:139], v[92:93], v[132:133], v[138:139]
	v_pk_fma_f32 v[136:137], v[94:95], v[126:127], v[136:137]
	v_pk_fma_f32 v[138:139], v[94:95], v[134:135], v[138:139]
	v_add_f32_e32 v108, v136, v137
	v_add_f32_e32 v109, v138, v139
	v_cvt_pk_f32_fp8_e32 v[120:121], v24
	v_cvt_pk_f32_fp8_sdwa v[122:123], v24 src0_sel:WORD_1
	v_cvt_pk_f32_fp8_e32 v[124:125], v25
	v_cvt_pk_f32_fp8_sdwa v[126:127], v25 src0_sel:WORD_1
	v_cvt_pk_f32_fp8_e32 v[128:129], v28
	v_cvt_pk_f32_fp8_sdwa v[130:131], v28 src0_sel:WORD_1
	v_cvt_pk_f32_fp8_e32 v[132:133], v29
	v_cvt_pk_f32_fp8_sdwa v[134:135], v29 src0_sel:WORD_1
	v_pk_mul_f32 v[136:137], v[80:81], v[120:121]
	v_pk_mul_f32 v[138:139], v[80:81], v[128:129]
	v_pk_fma_f32 v[136:137], v[82:83], v[122:123], v[136:137]
	v_pk_fma_f32 v[138:139], v[82:83], v[130:131], v[138:139]
	v_pk_fma_f32 v[136:137], v[84:85], v[124:125], v[136:137]
	v_pk_fma_f32 v[138:139], v[84:85], v[132:133], v[138:139]
	v_pk_fma_f32 v[136:137], v[86:87], v[126:127], v[136:137]
	v_pk_fma_f32 v[138:139], v[86:87], v[134:135], v[138:139]
	v_cvt_pk_f32_fp8_e32 v[120:121], v26
	v_cvt_pk_f32_fp8_sdwa v[122:123], v26 src0_sel:WORD_1
	v_cvt_pk_f32_fp8_e32 v[124:125], v27
	v_cvt_pk_f32_fp8_sdwa v[126:127], v27 src0_sel:WORD_1
	v_cvt_pk_f32_fp8_e32 v[128:129], v30
	v_cvt_pk_f32_fp8_sdwa v[130:131], v30 src0_sel:WORD_1
	v_cvt_pk_f32_fp8_e32 v[132:133], v31
	v_cvt_pk_f32_fp8_sdwa v[134:135], v31 src0_sel:WORD_1
	v_pk_fma_f32 v[136:137], v[88:89], v[120:121], v[136:137]
	v_pk_fma_f32 v[138:139], v[88:89], v[128:129], v[138:139]
	v_pk_fma_f32 v[136:137], v[90:91], v[122:123], v[136:137]
	v_pk_fma_f32 v[138:139], v[90:91], v[130:131], v[138:139]
	v_pk_fma_f32 v[136:137], v[92:93], v[124:125], v[136:137]
	v_pk_fma_f32 v[138:139], v[92:93], v[132:133], v[138:139]
	v_pk_fma_f32 v[136:137], v[94:95], v[126:127], v[136:137]
	v_pk_fma_f32 v[138:139], v[94:95], v[134:135], v[138:139]
	v_add_f32_e32 v110, v136, v137
	v_add_f32_e32 v111, v138, v139
	s_waitcnt lgkmcnt(0)
	global_load_dwordx4 v[96:99], v165, s[78:79]
	global_load_dwordx4 v[100:103], v165, s[78:79] offset:16
	v_add_u32_e32 v0, v64, v160
	v_add_u32_e32 v4, v65, v160
	v_add_u32_e32 v8, v66, v160
	v_add_u32_e32 v12, v67, v160
	v_add_u32_e32 v16, v68, v160
	v_add_u32_e32 v20, v69, v160
	v_add_u32_e32 v24, v70, v160
	v_add_u32_e32 v28, v71, v160
	global_load_dwordx4 v[0:3], v0, s[42:43]
	global_load_dwordx4 v[4:7], v4, s[42:43]
	global_load_dwordx4 v[8:11], v8, s[42:43]
	global_load_dwordx4 v[12:15], v12, s[42:43]
	global_load_dwordx4 v[16:19], v16, s[42:43]
	global_load_dwordx4 v[20:23], v20, s[42:43]
	global_load_dwordx4 v[24:27], v24, s[42:43]
	global_load_dwordx4 v[28:31], v28, s[42:43]
	s_waitcnt vmcnt(12)
	v_cvt_pk_f32_fp8_e32 v[120:121], v32
	v_cvt_pk_f32_fp8_sdwa v[122:123], v32 src0_sel:WORD_1
	v_cvt_pk_f32_fp8_e32 v[124:125], v33
	v_cvt_pk_f32_fp8_sdwa v[126:127], v33 src0_sel:WORD_1
	v_cvt_pk_f32_fp8_e32 v[128:129], v36
	v_cvt_pk_f32_fp8_sdwa v[130:131], v36 src0_sel:WORD_1
	v_cvt_pk_f32_fp8_e32 v[132:133], v37
	v_cvt_pk_f32_fp8_sdwa v[134:135], v37 src0_sel:WORD_1
	v_pk_mul_f32 v[136:137], v[80:81], v[120:121]
	v_pk_mul_f32 v[138:139], v[80:81], v[128:129]
	v_pk_fma_f32 v[136:137], v[82:83], v[122:123], v[136:137]
	v_pk_fma_f32 v[138:139], v[82:83], v[130:131], v[138:139]
	v_pk_fma_f32 v[136:137], v[84:85], v[124:125], v[136:137]
	v_pk_fma_f32 v[138:139], v[84:85], v[132:133], v[138:139]
	v_pk_fma_f32 v[136:137], v[86:87], v[126:127], v[136:137]
	v_pk_fma_f32 v[138:139], v[86:87], v[134:135], v[138:139]
	v_cvt_pk_f32_fp8_e32 v[120:121], v34
	v_cvt_pk_f32_fp8_sdwa v[122:123], v34 src0_sel:WORD_1
	v_cvt_pk_f32_fp8_e32 v[124:125], v35
	v_cvt_pk_f32_fp8_sdwa v[126:127], v35 src0_sel:WORD_1
	v_cvt_pk_f32_fp8_e32 v[128:129], v38
	v_cvt_pk_f32_fp8_sdwa v[130:131], v38 src0_sel:WORD_1
	v_cvt_pk_f32_fp8_e32 v[132:133], v39
	v_cvt_pk_f32_fp8_sdwa v[134:135], v39 src0_sel:WORD_1
	v_pk_fma_f32 v[136:137], v[88:89], v[120:121], v[136:137]
	v_pk_fma_f32 v[138:139], v[88:89], v[128:129], v[138:139]
	v_pk_fma_f32 v[136:137], v[90:91], v[122:123], v[136:137]
	v_pk_fma_f32 v[138:139], v[90:91], v[130:131], v[138:139]
	v_pk_fma_f32 v[136:137], v[92:93], v[124:125], v[136:137]
	v_pk_fma_f32 v[138:139], v[92:93], v[132:133], v[138:139]
	v_pk_fma_f32 v[136:137], v[94:95], v[126:127], v[136:137]
	v_pk_fma_f32 v[138:139], v[94:95], v[134:135], v[138:139]
	v_add_f32_e32 v112, v136, v137
	v_add_f32_e32 v113, v138, v139
	v_cvt_pk_f32_fp8_e32 v[120:121], v40
	v_cvt_pk_f32_fp8_sdwa v[122:123], v40 src0_sel:WORD_1
	v_cvt_pk_f32_fp8_e32 v[124:125], v41
	v_cvt_pk_f32_fp8_sdwa v[126:127], v41 src0_sel:WORD_1
	v_cvt_pk_f32_fp8_e32 v[128:129], v44
	v_cvt_pk_f32_fp8_sdwa v[130:131], v44 src0_sel:WORD_1
	v_cvt_pk_f32_fp8_e32 v[132:133], v45
	v_cvt_pk_f32_fp8_sdwa v[134:135], v45 src0_sel:WORD_1
	v_pk_mul_f32 v[136:137], v[80:81], v[120:121]
	v_pk_mul_f32 v[138:139], v[80:81], v[128:129]
	v_pk_fma_f32 v[136:137], v[82:83], v[122:123], v[136:137]
	v_pk_fma_f32 v[138:139], v[82:83], v[130:131], v[138:139]
	v_pk_fma_f32 v[136:137], v[84:85], v[124:125], v[136:137]
	v_pk_fma_f32 v[138:139], v[84:85], v[132:133], v[138:139]
	v_pk_fma_f32 v[136:137], v[86:87], v[126:127], v[136:137]
	v_pk_fma_f32 v[138:139], v[86:87], v[134:135], v[138:139]
	v_cvt_pk_f32_fp8_e32 v[120:121], v42
	v_cvt_pk_f32_fp8_sdwa v[122:123], v42 src0_sel:WORD_1
	v_cvt_pk_f32_fp8_e32 v[124:125], v43
	v_cvt_pk_f32_fp8_sdwa v[126:127], v43 src0_sel:WORD_1
	v_cvt_pk_f32_fp8_e32 v[128:129], v46
	v_cvt_pk_f32_fp8_sdwa v[130:131], v46 src0_sel:WORD_1
	v_cvt_pk_f32_fp8_e32 v[132:133], v47
	v_cvt_pk_f32_fp8_sdwa v[134:135], v47 src0_sel:WORD_1
	v_pk_fma_f32 v[136:137], v[88:89], v[120:121], v[136:137]
	v_pk_fma_f32 v[138:139], v[88:89], v[128:129], v[138:139]
	v_pk_fma_f32 v[136:137], v[90:91], v[122:123], v[136:137]
	v_pk_fma_f32 v[138:139], v[90:91], v[130:131], v[138:139]
	v_pk_fma_f32 v[136:137], v[92:93], v[124:125], v[136:137]
	v_pk_fma_f32 v[138:139], v[92:93], v[132:133], v[138:139]
	v_pk_fma_f32 v[136:137], v[94:95], v[126:127], v[136:137]
	v_pk_fma_f32 v[138:139], v[94:95], v[134:135], v[138:139]
	v_add_f32_e32 v114, v136, v137
	v_add_f32_e32 v115, v138, v139
	v_cvt_pk_f32_fp8_e32 v[120:121], v48
	v_cvt_pk_f32_fp8_sdwa v[122:123], v48 src0_sel:WORD_1
	v_cvt_pk_f32_fp8_e32 v[124:125], v49
	v_cvt_pk_f32_fp8_sdwa v[126:127], v49 src0_sel:WORD_1
	v_cvt_pk_f32_fp8_e32 v[128:129], v52
	v_cvt_pk_f32_fp8_sdwa v[130:131], v52 src0_sel:WORD_1
	v_cvt_pk_f32_fp8_e32 v[132:133], v53
	v_cvt_pk_f32_fp8_sdwa v[134:135], v53 src0_sel:WORD_1
	v_pk_mul_f32 v[136:137], v[80:81], v[120:121]
	v_pk_mul_f32 v[138:139], v[80:81], v[128:129]
	v_pk_fma_f32 v[136:137], v[82:83], v[122:123], v[136:137]
	v_pk_fma_f32 v[138:139], v[82:83], v[130:131], v[138:139]
	v_pk_fma_f32 v[136:137], v[84:85], v[124:125], v[136:137]
	v_pk_fma_f32 v[138:139], v[84:85], v[132:133], v[138:139]
	v_pk_fma_f32 v[136:137], v[86:87], v[126:127], v[136:137]
	v_pk_fma_f32 v[138:139], v[86:87], v[134:135], v[138:139]
	v_cvt_pk_f32_fp8_e32 v[120:121], v50
	v_cvt_pk_f32_fp8_sdwa v[122:123], v50 src0_sel:WORD_1
	v_cvt_pk_f32_fp8_e32 v[124:125], v51
	v_cvt_pk_f32_fp8_sdwa v[126:127], v51 src0_sel:WORD_1
	v_cvt_pk_f32_fp8_e32 v[128:129], v54
	v_cvt_pk_f32_fp8_sdwa v[130:131], v54 src0_sel:WORD_1
	v_cvt_pk_f32_fp8_e32 v[132:133], v55
	v_cvt_pk_f32_fp8_sdwa v[134:135], v55 src0_sel:WORD_1
	v_pk_fma_f32 v[136:137], v[88:89], v[120:121], v[136:137]
	v_pk_fma_f32 v[138:139], v[88:89], v[128:129], v[138:139]
	v_pk_fma_f32 v[136:137], v[90:91], v[122:123], v[136:137]
	v_pk_fma_f32 v[138:139], v[90:91], v[130:131], v[138:139]
	v_pk_fma_f32 v[136:137], v[92:93], v[124:125], v[136:137]
	v_pk_fma_f32 v[138:139], v[92:93], v[132:133], v[138:139]
	v_pk_fma_f32 v[136:137], v[94:95], v[126:127], v[136:137]
	v_pk_fma_f32 v[138:139], v[94:95], v[134:135], v[138:139]
	v_add_f32_e32 v116, v136, v137
	v_add_f32_e32 v117, v138, v139
	v_cvt_pk_f32_fp8_e32 v[120:121], v56
	v_cvt_pk_f32_fp8_sdwa v[122:123], v56 src0_sel:WORD_1
	v_cvt_pk_f32_fp8_e32 v[124:125], v57
	v_cvt_pk_f32_fp8_sdwa v[126:127], v57 src0_sel:WORD_1
	v_cvt_pk_f32_fp8_e32 v[128:129], v60
	v_cvt_pk_f32_fp8_sdwa v[130:131], v60 src0_sel:WORD_1
	v_cvt_pk_f32_fp8_e32 v[132:133], v61
	v_cvt_pk_f32_fp8_sdwa v[134:135], v61 src0_sel:WORD_1
	v_pk_mul_f32 v[136:137], v[80:81], v[120:121]
	v_pk_mul_f32 v[138:139], v[80:81], v[128:129]
; DI void phase_peer(const Params& p, int l, int bid, int nblk) {
;     ...
;     const float ga0 = gelu_tanh(act0 * (1.f / U_SCALE)) * g0 * (1.f / V_SCALE);
;     const float ga1 = gelu_tanh(act1 * (1.f / U_SCALE)) * g1 * (1.f / V_SCALE);
	v_pk_fma_f32 v[136:137], v[82:83], v[122:123], v[136:137]
	v_pk_fma_f32 v[138:139], v[82:83], v[130:131], v[138:139]
	v_pk_fma_f32 v[136:137], v[84:85], v[124:125], v[136:137]
	v_pk_fma_f32 v[138:139], v[84:85], v[132:133], v[138:139]
	v_pk_fma_f32 v[136:137], v[86:87], v[126:127], v[136:137]
	v_pk_fma_f32 v[138:139], v[86:87], v[134:135], v[138:139]
	v_cvt_pk_f32_fp8_e32 v[120:121], v58
	v_cvt_pk_f32_fp8_sdwa v[122:123], v58 src0_sel:WORD_1
	v_cvt_pk_f32_fp8_e32 v[124:125], v59
	v_cvt_pk_f32_fp8_sdwa v[126:127], v59 src0_sel:WORD_1
	v_cvt_pk_f32_fp8_e32 v[128:129], v62
	v_cvt_pk_f32_fp8_sdwa v[130:131], v62 src0_sel:WORD_1
	v_cvt_pk_f32_fp8_e32 v[132:133], v63
	v_cvt_pk_f32_fp8_sdwa v[134:135], v63 src0_sel:WORD_1
	v_pk_fma_f32 v[136:137], v[88:89], v[120:121], v[136:137]
	v_pk_fma_f32 v[138:139], v[88:89], v[128:129], v[138:139]
	v_pk_fma_f32 v[136:137], v[90:91], v[122:123], v[136:137]
	v_pk_fma_f32 v[138:139], v[90:91], v[130:131], v[138:139]
	v_pk_fma_f32 v[136:137], v[92:93], v[124:125], v[136:137]
	v_pk_fma_f32 v[138:139], v[92:93], v[132:133], v[138:139]
	v_pk_fma_f32 v[136:137], v[94:95], v[126:127], v[136:137]
	v_pk_fma_f32 v[138:139], v[94:95], v[134:135], v[138:139]
	v_add_f32_e32 v118, v136, v137
	v_add_f32_e32 v119, v138, v139
	v_add_u32_e32 v32, v72, v160
	v_add_u32_e32 v36, v73, v160
	v_add_u32_e32 v40, v74, v160
	v_add_u32_e32 v44, v75, v160
	v_add_u32_e32 v48, v76, v160
	v_add_u32_e32 v52, v77, v160
	v_add_u32_e32 v56, v78, v160
	v_add_u32_e32 v60, v79, v160
	global_load_dwordx4 v[32:35], v32, s[42:43]
	global_load_dwordx4 v[36:39], v36, s[42:43]
	global_load_dwordx4 v[40:43], v40, s[42:43]
	global_load_dwordx4 v[44:47], v44, s[42:43]
	global_load_dwordx4 v[48:51], v48, s[42:43]
	global_load_dwordx4 v[52:55], v52, s[42:43]
	global_load_dwordx4 v[56:59], v56, s[42:43]
	global_load_dwordx4 v[60:63], v60, s[42:43]
	v_cndmask_b32_e64 v120, v104, v105, s[34:35]
	v_cndmask_b32_e64 v128, v105, v104, s[34:35]
	v_cndmask_b32_e64 v121, v106, v107, s[34:35]
	v_cndmask_b32_e64 v129, v107, v106, s[34:35]
	v_cndmask_b32_e64 v122, v108, v109, s[34:35]
	v_cndmask_b32_e64 v130, v109, v108, s[34:35]
	v_cndmask_b32_e64 v123, v110, v111, s[34:35]
	v_cndmask_b32_e64 v131, v111, v110, s[34:35]
	v_cndmask_b32_e64 v124, v112, v113, s[34:35]
	v_cndmask_b32_e64 v132, v113, v112, s[34:35]
	v_cndmask_b32_e64 v125, v114, v115, s[34:35]
	v_cndmask_b32_e64 v133, v115, v114, s[34:35]
	v_cndmask_b32_e64 v126, v116, v117, s[34:35]
	v_cndmask_b32_e64 v134, v117, v116, s[34:35]
	v_cndmask_b32_e64 v127, v118, v119, s[34:35]
	v_cndmask_b32_e64 v135, v119, v118, s[34:35]
	v_add_f32_dpp v104, v128, v120 row_half_mirror row_mask:0xf bank_mask:0xf
	v_add_f32_dpp v105, v129, v121 row_half_mirror row_mask:0xf bank_mask:0xf
	v_add_f32_dpp v106, v130, v122 row_half_mirror row_mask:0xf bank_mask:0xf
	v_add_f32_dpp v107, v131, v123 row_half_mirror row_mask:0xf bank_mask:0xf
	v_add_f32_dpp v108, v132, v124 row_half_mirror row_mask:0xf bank_mask:0xf
	v_add_f32_dpp v109, v133, v125 row_half_mirror row_mask:0xf bank_mask:0xf
	v_add_f32_dpp v110, v134, v126 row_half_mirror row_mask:0xf bank_mask:0xf
	v_add_f32_dpp v111, v135, v127 row_half_mirror row_mask:0xf bank_mask:0xf
	s_nop 0
	v_cndmask_b32_e64 v120, v104, v105, s[36:37]
	v_cndmask_b32_e64 v128, v105, v104, s[36:37]
	v_cndmask_b32_e64 v121, v106, v107, s[36:37]
	v_cndmask_b32_e64 v129, v107, v106, s[36:37]
	v_cndmask_b32_e64 v122, v108, v109, s[36:37]
	v_cndmask_b32_e64 v130, v109, v108, s[36:37]
	v_cndmask_b32_e64 v123, v110, v111, s[36:37]
	v_cndmask_b32_e64 v131, v111, v110, s[36:37]
	v_add_f32_dpp v104, v128, v120 quad_perm:[1,0,3,2] row_mask:0xf bank_mask:0xf
	v_add_f32_dpp v105, v129, v121 quad_perm:[1,0,3,2] row_mask:0xf bank_mask:0xf
	v_add_f32_dpp v106, v130, v122 quad_perm:[1,0,3,2] row_mask:0xf bank_mask:0xf
	v_add_f32_dpp v107, v131, v123 quad_perm:[1,0,3,2] row_mask:0xf bank_mask:0xf
	s_nop 0
	v_cndmask_b32_e64 v120, v104, v105, s[38:39]
	v_cndmask_b32_e64 v128, v105, v104, s[38:39]
	v_cndmask_b32_e64 v121, v106, v107, s[38:39]
	v_cndmask_b32_e64 v129, v107, v106, s[38:39]
	s_nop 0
	v_add_f32_dpp v104, v128, v120 quad_perm:[2,3,0,1] row_mask:0xf bank_mask:0xf
	v_add_f32_dpp v105, v129, v121 quad_perm:[2,3,0,1] row_mask:0xf bank_mask:0xf
	s_nop 0
	v_add_f32_e32 v104, v104, v140
	v_add_f32_e32 v105, v105, v141
	s_cmp_eq_u32 s46, 7
	s_cbranch_scc0 .Lpeer_u_store
	s_waitcnt vmcnt(18)
	v_mul_f32_e32 v146, 0x3c800000, v104
	v_mul_f32_e32 v147, v146, v146
	v_fmaak_f32 v147, v147, v168, 0x3fcc422a
	v_mul_f32_e32 v147, v146, v147
	v_mul_f32_e32 v147, 0xbfb8aa3b, v147
	v_exp_f32_e32 v147, v147
	s_nop 0
	v_add_f32_e32 v147, 1.0, v147
	v_rcp_f32_e32 v147, v147
	v_mul_f32_e32 v146, v146, v142
	v_mul_f32_e32 v104, v146, v147
	v_mul_f32_e32 v149, 0x3c800000, v105
	v_mul_f32_e32 v150, v149, v149
	v_fmaak_f32 v150, v150, v168, 0x3fcc422a
	v_mul_f32_e32 v150, v149, v150
	v_mul_f32_e32 v150, 0xbfb8aa3b, v150
	v_exp_f32_e32 v150, v150
	s_nop 0
	v_add_f32_e32 v150, 1.0, v150
	v_rcp_f32_e32 v150, v150
	v_mul_f32_e32 v149, v149, v143
	v_mul_f32_e32 v105, v149, v150
; DI void phase_peer(const Params& p, int l, int bid, int nblk) {
;     ...
;     PEER_LOAD(0, 0, VB)
; #pragma unroll 1
;     for (int k = 0; k < 16; k += 2) {
;       PEER_LOAD(1, k + 1, VB)
;       __builtin_amdgcn_sched_barrier(0);
;       PEER_ACC(0, k)
;       { const int kn = (k + 2 < 16) ? k + 2 : 15; PEER_LOAD(0, kn, VB) }
;       __builtin_amdgcn_sched_barrier(0);
;       PEER_ACC(1, k + 1)
;     }
;     ...
;     const int b2 = row2 / TPB, pos2 = row2 % TPB;
;     const float* xr = xrow_ptr(p, false, b2, pos2);
;     float* xw = xrow_wptr(p, b2, pos2);
;     const float* ga = WSP(const float, OFF_MOD) + (size_t)(l * 17 + (pos2 < CTXL ? 16 : b2)) * 6144 + 5120;
.Lpeer_u_store:
	ds_write2_b32 v145, v104, v105 offset1:8
	s_mov_b32 s46, s62
	s_mov_b32 s47, s63
	s_mov_b32 s48, s64
	s_mov_b32 s50, s65
	s_add_i32 s49, s49, -1
	s_cmp_lg_u32 s49, 0
	s_cbranch_scc1 .Lpeer_u_top
	s_waitcnt vmcnt(0) lgkmcnt(0)
	s_add_u32 s44, s96, 0xfa00000
	s_addc_u32 s45, s97, 0
	s_mov_b32 s42, s44
	s_mov_b32 s43, s45
	s_mov_b32 s46, 0
	s_mov_b32 s47, 0
	s_mov_b32 s50, 0
	s_lshl_b32 s49, s75, 3
	s_cmp_ge_u32 s47, s55
	s_addc_u32 s48, s47, 0
	s_cmp_ge_u32 s48, s66
	s_addc_u32 s48, s48, 0
	s_lshl_b32 s48, s48, 11
	s_add_i32 s48, s48, s67
	v_add_u32_e32 v144, s50, v162
	ds_read_b128 v[64:67], v144
	ds_read_b128 v[68:71], v144 offset:16
	ds_read_b128 v[72:75], v144 offset:32
	ds_read_b128 v[76:79], v144 offset:48
	s_waitcnt lgkmcnt(0)
	v_add_u32_e32 v0, v64, v160
	v_add_u32_e32 v4, v65, v160
	v_add_u32_e32 v8, v66, v160
	v_add_u32_e32 v12, v67, v160
	v_add_u32_e32 v16, v68, v160
	v_add_u32_e32 v20, v69, v160
	v_add_u32_e32 v24, v70, v160
	v_add_u32_e32 v28, v71, v160
	global_load_dwordx4 v[0:3], v0, s[42:43]
	global_load_dwordx4 v[4:7], v4, s[42:43]
	global_load_dwordx4 v[8:11], v8, s[42:43]
	global_load_dwordx4 v[12:15], v12, s[42:43]
	global_load_dwordx4 v[16:19], v16, s[42:43]
	global_load_dwordx4 v[20:23], v20, s[42:43]
	global_load_dwordx4 v[24:27], v24, s[42:43]
	global_load_dwordx4 v[28:31], v28, s[42:43]
	v_add_u32_e32 v32, v72, v160
	v_add_u32_e32 v36, v73, v160
	v_add_u32_e32 v40, v74, v160
	v_add_u32_e32 v44, v75, v160
	v_add_u32_e32 v48, v76, v160
	v_add_u32_e32 v52, v77, v160
	v_add_u32_e32 v56, v78, v160
	v_add_u32_e32 v60, v79, v160
	global_load_dwordx4 v[32:35], v32, s[42:43]
	global_load_dwordx4 v[36:39], v36, s[42:43]
	global_load_dwordx4 v[40:43], v40, s[42:43]
	global_load_dwordx4 v[44:47], v44, s[42:43]
	global_load_dwordx4 v[48:51], v48, s[42:43]
	global_load_dwordx4 v[52:55], v52, s[42:43]
	global_load_dwordx4 v[56:59], v56, s[42:43]
	global_load_dwordx4 v[60:63], v60, s[42:43]
.Lpeer_v_top:
	s_add_i32 s63, s47, 1
	s_cmp_lt_u32 s63, s75
	s_cselect_b32 s63, s63, 0
	s_cselect_b32 s51, 0, 1
	s_add_i32 s62, s46, s51
	s_cmp_lt_u32 s62, 8
	s_cselect_b32 s62, s62, 7
	s_cselect_b32 s63, s63, s47
	s_cmp_ge_u32 s63, s55
	s_addc_u32 s64, s63, 0
	s_cmp_ge_u32 s64, s66
	s_addc_u32 s64, s64, 0
	s_lshl_b32 s64, s64, 11
	s_add_i32 s64, s64, s67
	s_lshl_b32 s65, s63, 9
	s_lshl_b32 s51, s62, 21
	s_add_u32 s42, s44, s51
	s_addc_u32 s43, s45, 0
	s_mul_hi_u32 s84, s48, 0x38e38e39
	s_lshr_b32 s84, s84, 9
	s_mul_i32 s85, s84, 0x900
	s_sub_u32 s85, s48, s85
	s_cmp_lt_u32 s85, 0x100
	s_cbranch_scc1 .Lpeer_v_ctx
	s_lshl_b32 s86, s84, 11
	s_add_i32 s86, s86, s85
	s_add_i32 s86, s86, 0xffffff00
	s_lshl_b32 s86, s86, 12
	s_add_u32 s80, s94, s86
	s_addc_u32 s81, s95, 0
	s_branch .Lpeer_v_ptr
.Lpeer_v_ctx:
	s_lshl_b32 s86, s84, 8
	s_add_i32 s86, s86, s85
	s_lshl_b32 s86, s86, 12
	s_add_u32 s80, s96, 0x17a00000
	s_addc_u32 s81, s97, 0
	s_add_u32 s80, s80, s86
	s_addc_u32 s81, s81, 0
	s_mov_b32 s84, 16
.Lpeer_v_ptr:
	s_cmp_lg_u64 s[70:71], 0
	s_cselect_b32 s86, 17, 0
	s_add_i32 s84, s84, s86
	s_mul_i32 s84, s84, 0x6000
	s_add_u32 s82, s96, 0x1be09000
	s_addc_u32 s83, s97, 0
	s_add_u32 s82, s82, s84
	s_addc_u32 s83, s83, 0
	s_lshl_b32 s86, s46, 9
	s_add_u32 s80, s80, s86
	s_addc_u32 s81, s81, 0
	s_add_u32 s82, s82, s86
	s_addc_u32 s83, s83, 0
	v_add_u32_e32 v144, s65, v162
	ds_read_b128 v[64:67], v144
	ds_read_b128 v[68:71], v144 offset:16
	ds_read_b128 v[72:75], v144 offset:32
	ds_read_b128 v[76:79], v144 offset:48
	v_add_u32_e32 v145, s50, v164
	ds_read_b128 v[80:83], v145
	ds_read_b128 v[84:87], v145 offset:16
	ds_read_b128 v[88:91], v145 offset:32
	ds_read_b128 v[92:95], v145 offset:48
	v_mov_b64_e32 v[96:97], 0
	v_mov_b64_e32 v[98:99], 0
	v_mov_b64_e32 v[100:101], 0
	v_mov_b64_e32 v[102:103], 0
	v_mov_b64_e32 v[104:105], 0
	v_mov_b64_e32 v[106:107], 0
	v_mov_b64_e32 v[108:109], 0
	v_mov_b64_e32 v[110:111], 0
	s_waitcnt vmcnt(8) lgkmcnt(0)
	v_cvt_pk_f32_fp8_e32 v[120:121], v0
	v_cvt_pk_f32_fp8_sdwa v[122:123], v0 src0_sel:WORD_1
	v_cvt_pk_f32_fp8_e32 v[124:125], v1
	v_cvt_pk_f32_fp8_sdwa v[126:127], v1 src0_sel:WORD_1
	v_pk_fma_f32 v[96:97], v[120:121], v[80:81], v[96:97] op_sel_hi:[1,0,1]
	v_pk_fma_f32 v[98:99], v[122:123], v[80:81], v[98:99] op_sel_hi:[1,0,1]
	v_pk_fma_f32 v[100:101], v[124:125], v[80:81], v[100:101] op_sel_hi:[1,0,1]
	v_pk_fma_f32 v[102:103], v[126:127], v[80:81], v[102:103] op_sel_hi:[1,0,1]
	v_cvt_pk_f32_fp8_e32 v[120:121], v2
	v_cvt_pk_f32_fp8_sdwa v[122:123], v2 src0_sel:WORD_1
	v_cvt_pk_f32_fp8_e32 v[124:125], v3
	v_cvt_pk_f32_fp8_sdwa v[126:127], v3 src0_sel:WORD_1
	v_pk_fma_f32 v[104:105], v[120:121], v[80:81], v[104:105] op_sel_hi:[1,0,1]
	v_pk_fma_f32 v[106:107], v[122:123], v[80:81], v[106:107] op_sel_hi:[1,0,1]
	v_pk_fma_f32 v[108:109], v[124:125], v[80:81], v[108:109] op_sel_hi:[1,0,1]
	v_pk_fma_f32 v[110:111], v[126:127], v[80:81], v[110:111] op_sel_hi:[1,0,1]
	v_cvt_pk_f32_fp8_e32 v[128:129], v4
	v_cvt_pk_f32_fp8_sdwa v[130:131], v4 src0_sel:WORD_1
	v_cvt_pk_f32_fp8_e32 v[132:133], v5
	v_cvt_pk_f32_fp8_sdwa v[134:135], v5 src0_sel:WORD_1
	v_pk_fma_f32 v[96:97], v[128:129], v[80:81], v[96:97] op_sel:[0,1,0]
	v_pk_fma_f32 v[98:99], v[130:131], v[80:81], v[98:99] op_sel:[0,1,0]
	v_pk_fma_f32 v[100:101], v[132:133], v[80:81], v[100:101] op_sel:[0,1,0]
	v_pk_fma_f32 v[102:103], v[134:135], v[80:81], v[102:103] op_sel:[0,1,0]
	v_cvt_pk_f32_fp8_e32 v[128:129], v6
	v_cvt_pk_f32_fp8_sdwa v[130:131], v6 src0_sel:WORD_1
	v_cvt_pk_f32_fp8_e32 v[132:133], v7
	v_cvt_pk_f32_fp8_sdwa v[134:135], v7 src0_sel:WORD_1
	v_pk_fma_f32 v[104:105], v[128:129], v[80:81], v[104:105] op_sel:[0,1,0]
	v_pk_fma_f32 v[106:107], v[130:131], v[80:81], v[106:107] op_sel:[0,1,0]
	v_pk_fma_f32 v[108:109], v[132:133], v[80:81], v[108:109] op_sel:[0,1,0]
	v_pk_fma_f32 v[110:111], v[134:135], v[80:81], v[110:111] op_sel:[0,1,0]
	v_cvt_pk_f32_fp8_e32 v[120:121], v8
	v_cvt_pk_f32_fp8_sdwa v[122:123], v8 src0_sel:WORD_1
	v_cvt_pk_f32_fp8_e32 v[124:125], v9
	v_cvt_pk_f32_fp8_sdwa v[126:127], v9 src0_sel:WORD_1
	v_pk_fma_f32 v[96:97], v[120:121], v[82:83], v[96:97] op_sel_hi:[1,0,1]
	v_pk_fma_f32 v[98:99], v[122:123], v[82:83], v[98:99] op_sel_hi:[1,0,1]
	v_pk_fma_f32 v[100:101], v[124:125], v[82:83], v[100:101] op_sel_hi:[1,0,1]
	v_pk_fma_f32 v[102:103], v[126:127], v[82:83], v[102:103] op_sel_hi:[1,0,1]
	v_cvt_pk_f32_fp8_e32 v[120:121], v10
	v_cvt_pk_f32_fp8_sdwa v[122:123], v10 src0_sel:WORD_1
	v_cvt_pk_f32_fp8_e32 v[124:125], v11
	v_cvt_pk_f32_fp8_sdwa v[126:127], v11 src0_sel:WORD_1
	v_pk_fma_f32 v[104:105], v[120:121], v[82:83], v[104:105] op_sel_hi:[1,0,1]
	v_pk_fma_f32 v[106:107], v[122:123], v[82:83], v[106:107] op_sel_hi:[1,0,1]
	v_pk_fma_f32 v[108:109], v[124:125], v[82:83], v[108:109] op_sel_hi:[1,0,1]
	v_pk_fma_f32 v[110:111], v[126:127], v[82:83], v[110:111] op_sel_hi:[1,0,1]
	v_cvt_pk_f32_fp8_e32 v[128:129], v12
	v_cvt_pk_f32_fp8_sdwa v[130:131], v12 src0_sel:WORD_1
	v_cvt_pk_f32_fp8_e32 v[132:133], v13
	v_cvt_pk_f32_fp8_sdwa v[134:135], v13 src0_sel:WORD_1
	v_pk_fma_f32 v[96:97], v[128:129], v[82:83], v[96:97] op_sel:[0,1,0]
	v_pk_fma_f32 v[98:99], v[130:131], v[82:83], v[98:99] op_sel:[0,1,0]
	v_pk_fma_f32 v[100:101], v[132:133], v[82:83], v[100:101] op_sel:[0,1,0]
	v_pk_fma_f32 v[102:103], v[134:135], v[82:83], v[102:103] op_sel:[0,1,0]
	v_cvt_pk_f32_fp8_e32 v[128:129], v14
	v_cvt_pk_f32_fp8_sdwa v[130:131], v14 src0_sel:WORD_1
	v_cvt_pk_f32_fp8_e32 v[132:133], v15
	v_cvt_pk_f32_fp8_sdwa v[134:135], v15 src0_sel:WORD_1
	v_pk_fma_f32 v[104:105], v[128:129], v[82:83], v[104:105] op_sel:[0,1,0]
	v_pk_fma_f32 v[106:107], v[130:131], v[82:83], v[106:107] op_sel:[0,1,0]
	v_pk_fma_f32 v[108:109], v[132:133], v[82:83], v[108:109] op_sel:[0,1,0]
	v_pk_fma_f32 v[110:111], v[134:135], v[82:83], v[110:111] op_sel:[0,1,0]
	v_cvt_pk_f32_fp8_e32 v[120:121], v16
	v_cvt_pk_f32_fp8_sdwa v[122:123], v16 src0_sel:WORD_1
	v_cvt_pk_f32_fp8_e32 v[124:125], v17
	v_cvt_pk_f32_fp8_sdwa v[126:127], v17 src0_sel:WORD_1
	v_pk_fma_f32 v[96:97], v[120:121], v[84:85], v[96:97] op_sel_hi:[1,0,1]
	v_pk_fma_f32 v[98:99], v[122:123], v[84:85], v[98:99] op_sel_hi:[1,0,1]
	v_pk_fma_f32 v[100:101], v[124:125], v[84:85], v[100:101] op_sel_hi:[1,0,1]
	v_pk_fma_f32 v[102:103], v[126:127], v[84:85], v[102:103] op_sel_hi:[1,0,1]
	v_cvt_pk_f32_fp8_e32 v[120:121], v18
	v_cvt_pk_f32_fp8_sdwa v[122:123], v18 src0_sel:WORD_1
	v_cvt_pk_f32_fp8_e32 v[124:125], v19
	v_cvt_pk_f32_fp8_sdwa v[126:127], v19 src0_sel:WORD_1
	v_pk_fma_f32 v[104:105], v[120:121], v[84:85], v[104:105] op_sel_hi:[1,0,1]
	v_pk_fma_f32 v[106:107], v[122:123], v[84:85], v[106:107] op_sel_hi:[1,0,1]
	v_pk_fma_f32 v[108:109], v[124:125], v[84:85], v[108:109] op_sel_hi:[1,0,1]
	v_pk_fma_f32 v[110:111], v[126:127], v[84:85], v[110:111] op_sel_hi:[1,0,1]
	v_cvt_pk_f32_fp8_e32 v[128:129], v20
	v_cvt_pk_f32_fp8_sdwa v[130:131], v20 src0_sel:WORD_1
	v_cvt_pk_f32_fp8_e32 v[132:133], v21
	v_cvt_pk_f32_fp8_sdwa v[134:135], v21 src0_sel:WORD_1
	v_pk_fma_f32 v[96:97], v[128:129], v[84:85], v[96:97] op_sel:[0,1,0]
	v_pk_fma_f32 v[98:99], v[130:131], v[84:85], v[98:99] op_sel:[0,1,0]
	v_pk_fma_f32 v[100:101], v[132:133], v[84:85], v[100:101] op_sel:[0,1,0]
	v_pk_fma_f32 v[102:103], v[134:135], v[84:85], v[102:103] op_sel:[0,1,0]
	v_cvt_pk_f32_fp8_e32 v[128:129], v22
	v_cvt_pk_f32_fp8_sdwa v[130:131], v22 src0_sel:WORD_1
	v_cvt_pk_f32_fp8_e32 v[132:133], v23
	v_cvt_pk_f32_fp8_sdwa v[134:135], v23 src0_sel:WORD_1
	v_pk_fma_f32 v[104:105], v[128:129], v[84:85], v[104:105] op_sel:[0,1,0]
	v_pk_fma_f32 v[106:107], v[130:131], v[84:85], v[106:107] op_sel:[0,1,0]
	v_pk_fma_f32 v[108:109], v[132:133], v[84:85], v[108:109] op_sel:[0,1,0]
	v_pk_fma_f32 v[110:111], v[134:135], v[84:85], v[110:111] op_sel:[0,1,0]
	v_cvt_pk_f32_fp8_e32 v[120:121], v24
	v_cvt_pk_f32_fp8_sdwa v[122:123], v24 src0_sel:WORD_1
	v_cvt_pk_f32_fp8_e32 v[124:125], v25
	v_cvt_pk_f32_fp8_sdwa v[126:127], v25 src0_sel:WORD_1
	v_pk_fma_f32 v[96:97], v[120:121], v[86:87], v[96:97] op_sel_hi:[1,0,1]
	v_pk_fma_f32 v[98:99], v[122:123], v[86:87], v[98:99] op_sel_hi:[1,0,1]
	v_pk_fma_f32 v[100:101], v[124:125], v[86:87], v[100:101] op_sel_hi:[1,0,1]
	v_pk_fma_f32 v[102:103], v[126:127], v[86:87], v[102:103] op_sel_hi:[1,0,1]
	v_cvt_pk_f32_fp8_e32 v[120:121], v26
	v_cvt_pk_f32_fp8_sdwa v[122:123], v26 src0_sel:WORD_1
	v_cvt_pk_f32_fp8_e32 v[124:125], v27
	v_cvt_pk_f32_fp8_sdwa v[126:127], v27 src0_sel:WORD_1
	v_pk_fma_f32 v[104:105], v[120:121], v[86:87], v[104:105] op_sel_hi:[1,0,1]
	v_pk_fma_f32 v[106:107], v[122:123], v[86:87], v[106:107] op_sel_hi:[1,0,1]
	v_pk_fma_f32 v[108:109], v[124:125], v[86:87], v[108:109] op_sel_hi:[1,0,1]
	v_pk_fma_f32 v[110:111], v[126:127], v[86:87], v[110:111] op_sel_hi:[1,0,1]
	v_cvt_pk_f32_fp8_e32 v[128:129], v28
	v_cvt_pk_f32_fp8_sdwa v[130:131], v28 src0_sel:WORD_1
	v_cvt_pk_f32_fp8_e32 v[132:133], v29
	v_cvt_pk_f32_fp8_sdwa v[134:135], v29 src0_sel:WORD_1
	v_pk_fma_f32 v[96:97], v[128:129], v[86:87], v[96:97] op_sel:[0,1,0]
	v_pk_fma_f32 v[98:99], v[130:131], v[86:87], v[98:99] op_sel:[0,1,0]
	v_pk_fma_f32 v[100:101], v[132:133], v[86:87], v[100:101] op_sel:[0,1,0]
	v_pk_fma_f32 v[102:103], v[134:135], v[86:87], v[102:103] op_sel:[0,1,0]
	v_cvt_pk_f32_fp8_e32 v[128:129], v30
	v_cvt_pk_f32_fp8_sdwa v[130:131], v30 src0_sel:WORD_1
	v_cvt_pk_f32_fp8_e32 v[132:133], v31
	v_cvt_pk_f32_fp8_sdwa v[134:135], v31 src0_sel:WORD_1
	v_pk_fma_f32 v[104:105], v[128:129], v[86:87], v[104:105] op_sel:[0,1,0]
	v_pk_fma_f32 v[106:107], v[130:131], v[86:87], v[106:107] op_sel:[0,1,0]
	v_pk_fma_f32 v[108:109], v[132:133], v[86:87], v[108:109] op_sel:[0,1,0]
	v_pk_fma_f32 v[110:111], v[134:135], v[86:87], v[110:111] op_sel:[0,1,0]
	global_load_dwordx2 v[140:141], v166, s[80:81]
	global_load_dwordx2 v[142:143], v166, s[82:83]
	v_add_u32_e32 v0, v64, v160
	v_add_u32_e32 v4, v65, v160
	v_add_u32_e32 v8, v66, v160
	v_add_u32_e32 v12, v67, v160
	v_add_u32_e32 v16, v68, v160
	v_add_u32_e32 v20, v69, v160
	v_add_u32_e32 v24, v70, v160
	v_add_u32_e32 v28, v71, v160
	global_load_dwordx4 v[0:3], v0, s[42:43]
	global_load_dwordx4 v[4:7], v4, s[42:43]
	global_load_dwordx4 v[8:11], v8, s[42:43]
	global_load_dwordx4 v[12:15], v12, s[42:43]
	global_load_dwordx4 v[16:19], v16, s[42:43]
	global_load_dwordx4 v[20:23], v20, s[42:43]
	global_load_dwordx4 v[24:27], v24, s[42:43]
	global_load_dwordx4 v[28:31], v28, s[42:43]
	s_waitcnt vmcnt(10)
	v_cvt_pk_f32_fp8_e32 v[120:121], v32
	v_cvt_pk_f32_fp8_sdwa v[122:123], v32 src0_sel:WORD_1
	v_cvt_pk_f32_fp8_e32 v[124:125], v33
	v_cvt_pk_f32_fp8_sdwa v[126:127], v33 src0_sel:WORD_1
	v_pk_fma_f32 v[96:97], v[120:121], v[88:89], v[96:97] op_sel_hi:[1,0,1]
	v_pk_fma_f32 v[98:99], v[122:123], v[88:89], v[98:99] op_sel_hi:[1,0,1]
	v_pk_fma_f32 v[100:101], v[124:125], v[88:89], v[100:101] op_sel_hi:[1,0,1]
	v_pk_fma_f32 v[102:103], v[126:127], v[88:89], v[102:103] op_sel_hi:[1,0,1]
	v_cvt_pk_f32_fp8_e32 v[120:121], v34
	v_cvt_pk_f32_fp8_sdwa v[122:123], v34 src0_sel:WORD_1
	v_cvt_pk_f32_fp8_e32 v[124:125], v35
	v_cvt_pk_f32_fp8_sdwa v[126:127], v35 src0_sel:WORD_1
	v_pk_fma_f32 v[104:105], v[120:121], v[88:89], v[104:105] op_sel_hi:[1,0,1]
	v_pk_fma_f32 v[106:107], v[122:123], v[88:89], v[106:107] op_sel_hi:[1,0,1]
	v_pk_fma_f32 v[108:109], v[124:125], v[88:89], v[108:109] op_sel_hi:[1,0,1]
	v_pk_fma_f32 v[110:111], v[126:127], v[88:89], v[110:111] op_sel_hi:[1,0,1]
	v_cvt_pk_f32_fp8_e32 v[128:129], v36
	v_cvt_pk_f32_fp8_sdwa v[130:131], v36 src0_sel:WORD_1
	v_cvt_pk_f32_fp8_e32 v[132:133], v37
	v_cvt_pk_f32_fp8_sdwa v[134:135], v37 src0_sel:WORD_1
	v_pk_fma_f32 v[96:97], v[128:129], v[88:89], v[96:97] op_sel:[0,1,0]
	v_pk_fma_f32 v[98:99], v[130:131], v[88:89], v[98:99] op_sel:[0,1,0]
	v_pk_fma_f32 v[100:101], v[132:133], v[88:89], v[100:101] op_sel:[0,1,0]
	v_pk_fma_f32 v[102:103], v[134:135], v[88:89], v[102:103] op_sel:[0,1,0]
	v_cvt_pk_f32_fp8_e32 v[128:129], v38
	v_cvt_pk_f32_fp8_sdwa v[130:131], v38 src0_sel:WORD_1
	v_cvt_pk_f32_fp8_e32 v[132:133], v39
	v_cvt_pk_f32_fp8_sdwa v[134:135], v39 src0_sel:WORD_1
	v_pk_fma_f32 v[104:105], v[128:129], v[88:89], v[104:105] op_sel:[0,1,0]
	v_pk_fma_f32 v[106:107], v[130:131], v[88:89], v[106:107] op_sel:[0,1,0]
	v_pk_fma_f32 v[108:109], v[132:133], v[88:89], v[108:109] op_sel:[0,1,0]
	v_pk_fma_f32 v[110:111], v[134:135], v[88:89], v[110:111] op_sel:[0,1,0]
	v_cvt_pk_f32_fp8_e32 v[120:121], v40
	v_cvt_pk_f32_fp8_sdwa v[122:123], v40 src0_sel:WORD_1
	v_cvt_pk_f32_fp8_e32 v[124:125], v41
	v_cvt_pk_f32_fp8_sdwa v[126:127], v41 src0_sel:WORD_1
	v_pk_fma_f32 v[96:97], v[120:121], v[90:91], v[96:97] op_sel_hi:[1,0,1]
	v_pk_fma_f32 v[98:99], v[122:123], v[90:91], v[98:99] op_sel_hi:[1,0,1]
	v_pk_fma_f32 v[100:101], v[124:125], v[90:91], v[100:101] op_sel_hi:[1,0,1]
	v_pk_fma_f32 v[102:103], v[126:127], v[90:91], v[102:103] op_sel_hi:[1,0,1]
	v_cvt_pk_f32_fp8_e32 v[120:121], v42
	v_cvt_pk_f32_fp8_sdwa v[122:123], v42 src0_sel:WORD_1
	v_cvt_pk_f32_fp8_e32 v[124:125], v43
	v_cvt_pk_f32_fp8_sdwa v[126:127], v43 src0_sel:WORD_1
	v_pk_fma_f32 v[104:105], v[120:121], v[90:91], v[104:105] op_sel_hi:[1,0,1]
	v_pk_fma_f32 v[106:107], v[122:123], v[90:91], v[106:107] op_sel_hi:[1,0,1]
	v_pk_fma_f32 v[108:109], v[124:125], v[90:91], v[108:109] op_sel_hi:[1,0,1]
	v_pk_fma_f32 v[110:111], v[126:127], v[90:91], v[110:111] op_sel_hi:[1,0,1]
	v_cvt_pk_f32_fp8_e32 v[128:129], v44
	v_cvt_pk_f32_fp8_sdwa v[130:131], v44 src0_sel:WORD_1
	v_cvt_pk_f32_fp8_e32 v[132:133], v45
	v_cvt_pk_f32_fp8_sdwa v[134:135], v45 src0_sel:WORD_1
	v_pk_fma_f32 v[96:97], v[128:129], v[90:91], v[96:97] op_sel:[0,1,0]
	v_pk_fma_f32 v[98:99], v[130:131], v[90:91], v[98:99] op_sel:[0,1,0]
	v_pk_fma_f32 v[100:101], v[132:133], v[90:91], v[100:101] op_sel:[0,1,0]
	v_pk_fma_f32 v[102:103], v[134:135], v[90:91], v[102:103] op_sel:[0,1,0]
	v_cvt_pk_f32_fp8_e32 v[128:129], v46
	v_cvt_pk_f32_fp8_sdwa v[130:131], v46 src0_sel:WORD_1
	v_cvt_pk_f32_fp8_e32 v[132:133], v47
	v_cvt_pk_f32_fp8_sdwa v[134:135], v47 src0_sel:WORD_1
	v_pk_fma_f32 v[104:105], v[128:129], v[90:91], v[104:105] op_sel:[0,1,0]
	v_pk_fma_f32 v[106:107], v[130:131], v[90:91], v[106:107] op_sel:[0,1,0]
	v_pk_fma_f32 v[108:109], v[132:133], v[90:91], v[108:109] op_sel:[0,1,0]
	v_pk_fma_f32 v[110:111], v[134:135], v[90:91], v[110:111] op_sel:[0,1,0]
	v_cvt_pk_f32_fp8_e32 v[120:121], v48
	v_cvt_pk_f32_fp8_sdwa v[122:123], v48 src0_sel:WORD_1
	v_cvt_pk_f32_fp8_e32 v[124:125], v49
	v_cvt_pk_f32_fp8_sdwa v[126:127], v49 src0_sel:WORD_1
	v_pk_fma_f32 v[96:97], v[120:121], v[92:93], v[96:97] op_sel_hi:[1,0,1]
	v_pk_fma_f32 v[98:99], v[122:123], v[92:93], v[98:99] op_sel_hi:[1,0,1]
	v_pk_fma_f32 v[100:101], v[124:125], v[92:93], v[100:101] op_sel_hi:[1,0,1]
	v_pk_fma_f32 v[102:103], v[126:127], v[92:93], v[102:103] op_sel_hi:[1,0,1]
	v_cvt_pk_f32_fp8_e32 v[120:121], v50
	v_cvt_pk_f32_fp8_sdwa v[122:123], v50 src0_sel:WORD_1
	v_cvt_pk_f32_fp8_e32 v[124:125], v51
	v_cvt_pk_f32_fp8_sdwa v[126:127], v51 src0_sel:WORD_1
	v_pk_fma_f32 v[104:105], v[120:121], v[92:93], v[104:105] op_sel_hi:[1,0,1]
	v_pk_fma_f32 v[106:107], v[122:123], v[92:93], v[106:107] op_sel_hi:[1,0,1]
	v_pk_fma_f32 v[108:109], v[124:125], v[92:93], v[108:109] op_sel_hi:[1,0,1]
	v_pk_fma_f32 v[110:111], v[126:127], v[92:93], v[110:111] op_sel_hi:[1,0,1]
	v_cvt_pk_f32_fp8_e32 v[128:129], v52
	v_cvt_pk_f32_fp8_sdwa v[130:131], v52 src0_sel:WORD_1
	v_cvt_pk_f32_fp8_e32 v[132:133], v53
	v_cvt_pk_f32_fp8_sdwa v[134:135], v53 src0_sel:WORD_1
	v_pk_fma_f32 v[96:97], v[128:129], v[92:93], v[96:97] op_sel:[0,1,0]
	v_pk_fma_f32 v[98:99], v[130:131], v[92:93], v[98:99] op_sel:[0,1,0]
	v_pk_fma_f32 v[100:101], v[132:133], v[92:93], v[100:101] op_sel:[0,1,0]
	v_pk_fma_f32 v[102:103], v[134:135], v[92:93], v[102:103] op_sel:[0,1,0]
	v_cvt_pk_f32_fp8_e32 v[128:129], v54
	v_cvt_pk_f32_fp8_sdwa v[130:131], v54 src0_sel:WORD_1
	v_cvt_pk_f32_fp8_e32 v[132:133], v55
	v_cvt_pk_f32_fp8_sdwa v[134:135], v55 src0_sel:WORD_1
	v_pk_fma_f32 v[104:105], v[128:129], v[92:93], v[104:105] op_sel:[0,1,0]
	v_pk_fma_f32 v[106:107], v[130:131], v[92:93], v[106:107] op_sel:[0,1,0]
; DI void phase_peer(const Params& p, int l, int bid, int nblk) {
;     ...
;     float xn[16];
;     float ss = 0.f;
; #pragma unroll
;     for (int q = 0; q < 4; ++q) {
;       const float4 xv = *(const float4*)(xr + lane2 * 16 + q * 4);
;       const float4 gv = *(const float4*)(ga + lane2 * 16 + q * 4);
;       xn[q * 4 + 0] = xv.x + gv.x * acc[q * 4 + 0];
;       xn[q * 4 + 1] = xv.y + gv.y * acc[q * 4 + 1];
;       xn[q * 4 + 2] = xv.z + gv.z * acc[q * 4 + 2];
;       xn[q * 4 + 3] = xv.w + gv.w * acc[q * 4 + 3];
;     }
;     if (l == 1) {
; #pragma unroll
;       for (int i = 0; i < 16; ++i) ss += xn[i] * xn[i];
;       ss = wave_sum(ss);
;       const float rs = rsqrtf(ss * (1.f / 1024.f) + EPSF);
; #pragma unroll
;       for (int i = 0; i < 16; ++i) xn[i] = xn[i] * rs * gfin[lane2 * 16 + i];
;     }
; #pragma unroll
;     for (int q = 0; q < 4; ++q) {
;       float4 o = {xn[q * 4 + 0], xn[q * 4 + 1], xn[q * 4 + 2], xn[q * 4 + 3]};
;       *(float4*)(xw + lane2 * 16 + q * 4) = o;
;     }
	v_pk_fma_f32 v[108:109], v[132:133], v[92:93], v[108:109] op_sel:[0,1,0]
	v_pk_fma_f32 v[110:111], v[134:135], v[92:93], v[110:111] op_sel:[0,1,0]
	v_cvt_pk_f32_fp8_e32 v[120:121], v56
	v_cvt_pk_f32_fp8_sdwa v[122:123], v56 src0_sel:WORD_1
	v_cvt_pk_f32_fp8_e32 v[124:125], v57
	v_cvt_pk_f32_fp8_sdwa v[126:127], v57 src0_sel:WORD_1
	v_pk_fma_f32 v[96:97], v[120:121], v[94:95], v[96:97] op_sel_hi:[1,0,1]
	v_pk_fma_f32 v[98:99], v[122:123], v[94:95], v[98:99] op_sel_hi:[1,0,1]
	v_pk_fma_f32 v[100:101], v[124:125], v[94:95], v[100:101] op_sel_hi:[1,0,1]
	v_pk_fma_f32 v[102:103], v[126:127], v[94:95], v[102:103] op_sel_hi:[1,0,1]
	v_cvt_pk_f32_fp8_e32 v[120:121], v58
	v_cvt_pk_f32_fp8_sdwa v[122:123], v58 src0_sel:WORD_1
	v_cvt_pk_f32_fp8_e32 v[124:125], v59
	v_cvt_pk_f32_fp8_sdwa v[126:127], v59 src0_sel:WORD_1
	v_pk_fma_f32 v[104:105], v[120:121], v[94:95], v[104:105] op_sel_hi:[1,0,1]
	v_pk_fma_f32 v[106:107], v[122:123], v[94:95], v[106:107] op_sel_hi:[1,0,1]
	v_pk_fma_f32 v[108:109], v[124:125], v[94:95], v[108:109] op_sel_hi:[1,0,1]
	v_pk_fma_f32 v[110:111], v[126:127], v[94:95], v[110:111] op_sel_hi:[1,0,1]
	v_cvt_pk_f32_fp8_e32 v[128:129], v60
	v_cvt_pk_f32_fp8_sdwa v[130:131], v60 src0_sel:WORD_1
	v_cvt_pk_f32_fp8_e32 v[132:133], v61
	v_cvt_pk_f32_fp8_sdwa v[134:135], v61 src0_sel:WORD_1
	v_pk_fma_f32 v[96:97], v[128:129], v[94:95], v[96:97] op_sel:[0,1,0]
	v_pk_fma_f32 v[98:99], v[130:131], v[94:95], v[98:99] op_sel:[0,1,0]
	v_pk_fma_f32 v[100:101], v[132:133], v[94:95], v[100:101] op_sel:[0,1,0]
	v_pk_fma_f32 v[102:103], v[134:135], v[94:95], v[102:103] op_sel:[0,1,0]
	v_cvt_pk_f32_fp8_e32 v[128:129], v62
	v_cvt_pk_f32_fp8_sdwa v[130:131], v62 src0_sel:WORD_1
	v_cvt_pk_f32_fp8_e32 v[132:133], v63
	v_cvt_pk_f32_fp8_sdwa v[134:135], v63 src0_sel:WORD_1
	v_pk_fma_f32 v[104:105], v[128:129], v[94:95], v[104:105] op_sel:[0,1,0]
	v_pk_fma_f32 v[106:107], v[130:131], v[94:95], v[106:107] op_sel:[0,1,0]
	v_pk_fma_f32 v[108:109], v[132:133], v[94:95], v[108:109] op_sel:[0,1,0]
	v_pk_fma_f32 v[110:111], v[134:135], v[94:95], v[110:111] op_sel:[0,1,0]
	v_add_u32_e32 v32, v72, v160
	v_add_u32_e32 v36, v73, v160
	v_add_u32_e32 v40, v74, v160
	v_add_u32_e32 v44, v75, v160
	v_add_u32_e32 v48, v76, v160
	v_add_u32_e32 v52, v77, v160
	v_add_u32_e32 v56, v78, v160
	v_add_u32_e32 v60, v79, v160
	global_load_dwordx4 v[32:35], v32, s[42:43]
	global_load_dwordx4 v[36:39], v36, s[42:43]
	global_load_dwordx4 v[40:43], v40, s[42:43]
	global_load_dwordx4 v[44:47], v44, s[42:43]
	global_load_dwordx4 v[48:51], v48, s[42:43]
	global_load_dwordx4 v[52:55], v52, s[42:43]
	global_load_dwordx4 v[56:59], v56, s[42:43]
	global_load_dwordx4 v[60:63], v60, s[42:43]
	s_nop 1
	v_permlane32_swap_b32 v96, v104
	v_permlane32_swap_b32 v97, v105
	v_permlane32_swap_b32 v98, v106
	v_permlane32_swap_b32 v99, v107
	v_permlane32_swap_b32 v100, v108
	v_permlane32_swap_b32 v101, v109
	v_permlane32_swap_b32 v102, v110
	v_permlane32_swap_b32 v103, v111
	v_pk_add_f32 v[96:97], v[96:97], v[104:105]
	v_pk_add_f32 v[98:99], v[98:99], v[106:107]
	v_pk_add_f32 v[100:101], v[100:101], v[108:109]
	v_pk_add_f32 v[102:103], v[102:103], v[110:111]
	s_nop 0
	v_permlane16_swap_b32 v96, v100
	v_permlane16_swap_b32 v97, v101
	v_permlane16_swap_b32 v98, v102
	v_permlane16_swap_b32 v99, v103
	v_pk_add_f32 v[96:97], v[96:97], v[100:101]
	v_pk_add_f32 v[98:99], v[98:99], v[102:103]
	v_cndmask_b32_e64 v120, v96, v98, s[40:41]
	v_cndmask_b32_e64 v121, v97, v99, s[40:41]
	v_cndmask_b32_e64 v122, v98, v96, s[40:41]
	v_cndmask_b32_e64 v123, v99, v97, s[40:41]
	s_nop 1
	v_add_f32_dpp v124, v122, v120 row_ror:8 row_mask:0xf bank_mask:0xf
	v_add_f32_dpp v125, v123, v121 row_ror:8 row_mask:0xf bank_mask:0xf
	s_waitcnt vmcnt(16)
	v_pk_fma_f32 v[140:141], v[142:143], v[124:125], v[140:141]
	s_nop 0
	global_store_dwordx2 v166, v[140:141], s[80:81]
	s_mov_b32 s46, s62
	s_mov_b32 s47, s63
	s_mov_b32 s48, s64
	s_mov_b32 s50, s65
	s_add_i32 s49, s49, -1
	s_cmp_lg_u32 s49, 0
	s_cbranch_scc1 .Lpeer_v_top
	s_waitcnt vmcnt(0) lgkmcnt(0)
	s_cmp_eq_u64 s[70:71], 0
	s_cbranch_scc1 .Lpeer_e_done
	v_lshlrev_b32_e32 v144, 4, v161
	global_load_dwordx4 v[16:19], v144, s[92:93]
	global_load_dwordx4 v[20:23], v144, s[92:93] offset:1024
	global_load_dwordx4 v[24:27], v144, s[92:93] offset:2048
	global_load_dwordx4 v[28:31], v144, s[92:93] offset:3072
	v_xor_b32_e32 v145, 16, v161
	v_xor_b32_e32 v146, 32, v161
	v_lshlrev_b32_e32 v145, 2, v145
	v_lshlrev_b32_e32 v146, 2, v146
	s_mov_b32 s47, 0
; DI void phase_peer(const Params& p, int l, int bid, int nblk) {
;     ...
;     if (l == 1) {
; #pragma unroll
;       for (int i = 0; i < 16; ++i) ss += xn[i] * xn[i];
;       ss = wave_sum(ss);
;       const float rs = rsqrtf(ss * (1.f / 1024.f) + EPSF);
; #pragma unroll
;       for (int i = 0; i < 16; ++i) xn[i] = xn[i] * rs * gfin[lane2 * 16 + i];
;     }
; #pragma unroll
;     for (int q = 0; q < 4; ++q) {
;       float4 o = {xn[q * 4 + 0], xn[q * 4 + 1], xn[q * 4 + 2], xn[q * 4 + 3]};
;       *(float4*)(xw + lane2 * 16 + q * 4) = o;
;     }
.Lpeer_e_top:
	s_cmp_ge_u32 s47, s55
	s_addc_u32 s48, s47, 0
	s_cmp_ge_u32 s48, s66
	s_addc_u32 s48, s48, 0
	s_lshl_b32 s48, s48, 11
	s_add_i32 s48, s48, s67
	s_mul_hi_u32 s84, s48, 0x38e38e39
	s_lshr_b32 s84, s84, 9
	s_mul_i32 s85, s84, 0x900
	s_sub_u32 s85, s48, s85
	s_lshl_b32 s86, s84, 11
	s_add_i32 s86, s86, s85
	s_add_i32 s86, s86, 0xffffff00
	s_lshl_b32 s86, s86, 12
	s_add_u32 s80, s94, s86
	s_addc_u32 s81, s95, 0
	global_load_dwordx4 v[32:35], v144, s[80:81] sc1
	global_load_dwordx4 v[36:39], v144, s[80:81] offset:1024 sc1
	global_load_dwordx4 v[40:43], v144, s[80:81] offset:2048 sc1
	global_load_dwordx4 v[44:47], v144, s[80:81] offset:3072 sc1
	s_waitcnt vmcnt(0)
	v_mul_f32_e32 v147, v32, v32
	v_fmac_f32_e32 v147, v33, v33
	v_fmac_f32_e32 v147, v34, v34
	v_fmac_f32_e32 v147, v35, v35
	v_fmac_f32_e32 v147, v36, v36
	v_fmac_f32_e32 v147, v37, v37
	v_fmac_f32_e32 v147, v38, v38
	v_fmac_f32_e32 v147, v39, v39
	v_fmac_f32_e32 v147, v40, v40
	v_fmac_f32_e32 v147, v41, v41
	v_fmac_f32_e32 v147, v42, v42
	v_fmac_f32_e32 v147, v43, v43
	v_fmac_f32_e32 v147, v44, v44
	v_fmac_f32_e32 v147, v45, v45
	v_fmac_f32_e32 v147, v46, v46
	v_fmac_f32_e32 v147, v47, v47
	s_nop 1
	v_add_f32_dpp v147, v147, v147 quad_perm:[1,0,3,2] row_mask:0xf bank_mask:0xf
	s_nop 1
	v_add_f32_dpp v147, v147, v147 quad_perm:[2,3,0,1] row_mask:0xf bank_mask:0xf
	s_nop 1
	v_add_f32_dpp v147, v147, v147 row_half_mirror row_mask:0xf bank_mask:0xf
	s_nop 1
	v_add_f32_dpp v147, v147, v147 row_mirror row_mask:0xf bank_mask:0xf
	s_nop 1
	ds_bpermute_b32 v148, v145, v147
	s_waitcnt lgkmcnt(0)
	v_add_f32_e32 v147, v147, v148
	ds_bpermute_b32 v148, v146, v147
	s_waitcnt lgkmcnt(0)
	v_add_f32_e32 v147, v147, v148
	v_mov_b32_e32 v148, 0x358637bd
	v_fmac_f32_e32 v148, 0x3a800000, v147
	v_rsq_f32_e32 v148, v148
	s_nop 0
	v_mul_f32_e32 v32, v32, v148
	v_mul_f32_e32 v33, v33, v148
	v_mul_f32_e32 v34, v34, v148
	v_mul_f32_e32 v35, v35, v148
	v_mul_f32_e32 v36, v36, v148
	v_mul_f32_e32 v37, v37, v148
	v_mul_f32_e32 v38, v38, v148
	v_mul_f32_e32 v39, v39, v148
	v_mul_f32_e32 v40, v40, v148
	v_mul_f32_e32 v41, v41, v148
	v_mul_f32_e32 v42, v42, v148
	v_mul_f32_e32 v43, v43, v148
	v_mul_f32_e32 v44, v44, v148
	v_mul_f32_e32 v45, v45, v148
	v_mul_f32_e32 v46, v46, v148
	v_mul_f32_e32 v47, v47, v148
	v_mul_f32_e32 v32, v32, v16
	v_mul_f32_e32 v33, v33, v17
	v_mul_f32_e32 v34, v34, v18
	v_mul_f32_e32 v35, v35, v19
	v_mul_f32_e32 v36, v36, v20
	v_mul_f32_e32 v37, v37, v21
	v_mul_f32_e32 v38, v38, v22
	v_mul_f32_e32 v39, v39, v23
	v_mul_f32_e32 v40, v40, v24
	v_mul_f32_e32 v41, v41, v25
	v_mul_f32_e32 v42, v42, v26
	v_mul_f32_e32 v43, v43, v27
	v_mul_f32_e32 v44, v44, v28
	v_mul_f32_e32 v45, v45, v29
	v_mul_f32_e32 v46, v46, v30
	v_mul_f32_e32 v47, v47, v31
	global_store_dwordx4 v144, v[32:35], s[80:81]
	global_store_dwordx4 v144, v[36:39], s[80:81] offset:1024
	global_store_dwordx4 v144, v[40:43], s[80:81] offset:2048
	global_store_dwordx4 v144, v[44:47], s[80:81] offset:3072
	s_add_i32 s47, s47, 1
	s_cmp_lt_u32 s47, s75
	s_cbranch_scc1 .Lpeer_e_top
.Lpeer_e_done:
	s_cmp_eq_u32 s72, 3
	s_cbranch_scc0 .Lpeer_norestore
	v_mov_b32_e32 v2, 0x11fe0
	v_mov_b32_e32 v3, s73
	v_mov_b32_e32 v4, s74
	ds_write_b32 v2, v3
	ds_write_b32 v2, v4 offset:4
.Lpeer_norestore:
	s_waitcnt vmcnt(0) lgkmcnt(0)
	v_readlane_b32 s0, v254, 8
	v_readlane_b32 s1, v254, 9
	s_mov_b64 s[70:71], -1
	s_andn2_b64 vcc, exec, s[0:1]
	s_mov_b64 s[0:1], -1
	s_cbranch_vccz .LBB0_1559
	s_getpc_b64 s[98:99]
